# adds: GLU epilogue and ret_out silu via rcp; first grid sync uses the XCD barrier instead of cooperative-groups sync
# speedup vs baseline: 1.0278x; 1.0175x over previous
; __device__ __forceinline__ unsigned pk_bf16(float lo, float hi) { unsigned r; asm volatile("v_cvt_pk_bf16_f32 %0, %1, %2" : "=v"(r) : "v"(lo), "v"(hi)); return r; }
; __device__ __forceinline__ float sigm_f(float x) { return 1.0f / (1.0f + __expf(-x)); }
;     __device__ __forceinline__ void operator()(const f32x4 (&acc)[2][2][4][2], const Unit& u, int wr, int wc, int fr, int fq) const {
;     ...
;         const int row0 = u.pm * BM + wr * 64 + fr, col0 = u.pn * HALF + wc * 32 + 8 * fq;
; #pragma unroll
;         for (int ai = 0; ai < 2; ++ai)
; #pragma unroll
;             for (int m = 0; m < 4; ++m) { bf16_t* rowp = C + (size_t)(row0 + ai * HALF + m * 16) * DM + col0;
;                 float o[8];
; #pragma unroll
;                 for (int n = 0; n < 2; ++n) { const f32x4 za = acc[ai][0][m][n], zb = acc[ai][1][m][n];
; #pragma unroll
;                     for (int j = 0; j < 4; ++j) o[4 * n + j] = za[j] * sigm_f(zb[j]); }
;                 u32x4 w; w.x = pk_bf16(o[0], o[1]); w.y = pk_bf16(o[2], o[3]); w.z = pk_bf16(o[4], o[5]); w.w = pk_bf16(o[6], o[7]);
;                 *(u32x4*)rowp = w; }
.LBB0_56:
	v_lshl_add_u32 v158, s50, 8, v140
	v_ashrrev_i32_e32 v159, 31, v158
	v_lshlrev_b64 v[156:157], 12, v[158:159]
	v_lshl_add_u64 v[160:161], s[16:17], 0, v[156:157]
	v_mul_f32_e32 v156, 0xbfb8aa3b, v44
	v_exp_f32_e32 v156, v156
	v_lshl_or_b32 v154, s4, 7, v133
	v_ashrrev_i32_e32 v155, 31, v154
	v_mul_f32_e32 v124, 0xbfb8aa3b, v124
	v_add_f32_e32 v156, 1.0, v156
	v_exp_f32_e32 v124, v124
	v_mul_f32_e32 v116, 0xbfb8aa3b, v116
	v_exp_f32_e32 v116, v116
	v_rcp_f32_e32 v156, v156
	s_nop 0
	v_mul_f32_e32 v159, v68, v156
	v_mul_f32_e32 v156, 0xbfb8aa3b, v45
	v_exp_f32_e32 v156, v156
	v_add_f32_e32 v124, 1.0, v124
	v_add_f32_e32 v116, 1.0, v116
	v_mul_f32_e32 v108, 0xbfb8aa3b, v108
	v_add_f32_e32 v156, 1.0, v156
	v_exp_f32_e32 v108, v108
	v_mul_f32_e32 v100, 0xbfb8aa3b, v100
	v_exp_f32_e32 v100, v100
	v_rcp_f32_e32 v156, v156
	s_nop 0
	v_mul_f32_e32 v180, v69, v156
	v_mul_f32_e32 v156, 0xbfb8aa3b, v46
	v_exp_f32_e32 v156, v156
	v_cvt_pk_bf16_f32 v180, v159, v180
	v_mul_f32_e32 v159, 0xbfb8aa3b, v24
	v_exp_f32_e32 v159, v159
	v_add_f32_e32 v156, 1.0, v156
	v_add_f32_e32 v159, 1.0, v159
	v_add_f32_e32 v108, 1.0, v108
	v_add_f32_e32 v100, 1.0, v100
	v_rcp_f32_e32 v156, v156
	s_nop 0
	v_mul_f32_e32 v181, v70, v156
	v_mul_f32_e32 v156, 0xbfb8aa3b, v47
	v_exp_f32_e32 v156, v156
	v_mul_f32_e32 v92, 0xbfb8aa3b, v92
	v_exp_f32_e32 v92, v92
	s_mov_b32 s5, 0x90000
	v_add_f32_e32 v156, 1.0, v156
	v_add_f32_e32 v92, 1.0, v92
	v_mul_f32_e32 v84, 0xbfb8aa3b, v84
	v_exp_f32_e32 v84, v84
	v_rcp_f32_e32 v156, v156
	s_nop 0
	v_mul_f32_e32 v182, v71, v156
	v_mul_f32_e32 v156, 0xbfb8aa3b, v36
	v_exp_f32_e32 v156, v156
	v_cvt_pk_bf16_f32 v181, v181, v182
	v_add_f32_e32 v84, 1.0, v84
	v_mul_f32_e32 v76, 0xbfb8aa3b, v76
	v_add_f32_e32 v156, 1.0, v156
	v_exp_f32_e32 v76, v76
	v_mul_f32_e32 v28, 0xbfb8aa3b, v28
	v_exp_f32_e32 v28, v28
	v_rcp_f32_e32 v156, v156
	s_nop 0
	v_mul_f32_e32 v183, v64, v156
	v_mul_f32_e32 v156, 0xbfb8aa3b, v37
	v_exp_f32_e32 v156, v156
	v_add_f32_e32 v76, 1.0, v76
	v_add_f32_e32 v28, 1.0, v28
	v_add_f32_e32 v156, 1.0, v156
	s_nop 0
	v_rcp_f32_e32 v156, v156
	s_nop 0
	v_mul_f32_e32 v184, v65, v156
	v_mul_f32_e32 v156, 0xbfb8aa3b, v38
	v_exp_f32_e32 v156, v156
	v_cvt_pk_bf16_f32 v182, v183, v184
	s_nop 0
	v_add_f32_e32 v156, 1.0, v156
	s_nop 0
	v_rcp_f32_e32 v156, v156
	s_nop 0
	v_mul_f32_e32 v185, v66, v156
	v_mul_f32_e32 v156, 0xbfb8aa3b, v39
	v_exp_f32_e32 v156, v156
	s_nop 0
	v_add_f32_e32 v156, 1.0, v156
	s_nop 0
	v_rcp_f32_e32 v156, v156
	s_nop 0
	v_mul_f32_e32 v186, v67, v156
	v_lshlrev_b64 v[156:157], 1, v[154:155]
	v_lshl_add_u64 v[154:155], v[160:161], 0, v[156:157]
	v_cvt_pk_bf16_f32 v183, v185, v186
	global_store_dwordx4 v[154:155], v[180:183], off
	v_or_b32_e32 v160, 16, v158
	v_ashrrev_i32_e32 v161, 31, v160
	v_lshlrev_b64 v[160:161], 12, v[160:161]
	v_lshl_add_u64 v[160:161], s[16:17], 0, v[160:161]
	v_lshl_add_u64 v[160:161], v[160:161], 0, v[156:157]
	v_rcp_f32_e32 v159, v159
	v_mul_f32_e32 v180, 0xbfb8aa3b, v25
	v_exp_f32_e32 v180, v180
	v_mul_f32_e32 v159, v60, v159
	v_add_f32_e32 v180, 1.0, v180
	s_nop 0
	v_rcp_f32_e32 v180, v180
	v_mul_f32_e32 v181, 0xbfb8aa3b, v26
	v_exp_f32_e32 v181, v181
	v_mul_f32_e32 v180, v61, v180
	v_cvt_pk_bf16_f32 v180, v159, v180
	v_mul_f32_e32 v159, 0xbfb8aa3b, v12
	v_add_f32_e32 v181, 1.0, v181
	v_exp_f32_e32 v159, v159
	v_rcp_f32_e32 v181, v181
	v_mul_f32_e32 v182, 0xbfb8aa3b, v27
	v_exp_f32_e32 v182, v182
	v_mul_f32_e32 v181, v62, v181
	v_add_f32_e32 v159, 1.0, v159
	v_add_f32_e32 v182, 1.0, v182
	s_nop 0
	v_rcp_f32_e32 v182, v182
	v_mul_f32_e32 v183, 0xbfb8aa3b, v20
	v_exp_f32_e32 v183, v183
	v_mul_f32_e32 v182, v63, v182
	v_cvt_pk_bf16_f32 v181, v181, v182
	v_add_f32_e32 v183, 1.0, v183
	s_nop 0
	v_rcp_f32_e32 v183, v183
	v_mul_f32_e32 v184, 0xbfb8aa3b, v21
	v_exp_f32_e32 v184, v184
	v_mul_f32_e32 v183, v56, v183
	v_add_f32_e32 v184, 1.0, v184
	s_nop 0
	v_rcp_f32_e32 v184, v184
	v_mul_f32_e32 v185, 0xbfb8aa3b, v22
	v_exp_f32_e32 v185, v185
	v_mul_f32_e32 v184, v57, v184
	v_cvt_pk_bf16_f32 v182, v183, v184
	v_add_f32_e32 v185, 1.0, v185
	s_nop 0
	v_rcp_f32_e32 v185, v185
	v_mul_f32_e32 v186, 0xbfb8aa3b, v23
	v_exp_f32_e32 v186, v186
	v_mul_f32_e32 v185, v58, v185
	v_add_f32_e32 v186, 1.0, v186
	s_nop 0
	v_rcp_f32_e32 v186, v186
	s_nop 0
	v_mul_f32_e32 v186, v59, v186
	v_cvt_pk_bf16_f32 v183, v185, v186
	global_store_dwordx4 v[160:161], v[180:183], off
	v_or_b32_e32 v160, 32, v158
	v_ashrrev_i32_e32 v161, 31, v160
	v_lshlrev_b64 v[160:161], 12, v[160:161]
	v_lshl_add_u64 v[160:161], s[16:17], 0, v[160:161]
	v_lshl_add_u64 v[160:161], v[160:161], 0, v[156:157]
	v_rcp_f32_e32 v159, v159
	v_mul_f32_e32 v180, 0xbfb8aa3b, v13
	v_exp_f32_e32 v180, v180
	v_mul_f32_e32 v159, v52, v159
	v_or_b32_e32 v158, 48, v158
	v_add_f32_e32 v180, 1.0, v180
	s_nop 0
	v_rcp_f32_e32 v180, v180
	v_mul_f32_e32 v181, 0xbfb8aa3b, v14
	v_exp_f32_e32 v181, v181
	v_mul_f32_e32 v180, v53, v180
	v_cvt_pk_bf16_f32 v180, v159, v180
	v_ashrrev_i32_e32 v159, 31, v158
	v_add_f32_e32 v181, 1.0, v181
	v_lshlrev_b64 v[158:159], 12, v[158:159]
	v_lshl_add_u64 v[158:159], s[16:17], 0, v[158:159]
	v_rcp_f32_e32 v181, v181
	v_mul_f32_e32 v182, 0xbfb8aa3b, v15
	v_exp_f32_e32 v182, v182
	v_mul_f32_e32 v181, v54, v181
	v_add_f32_e32 v182, 1.0, v182
	s_nop 0
	v_rcp_f32_e32 v182, v182
	v_mul_f32_e32 v183, 0xbfb8aa3b, v8
	v_exp_f32_e32 v183, v183
	v_mul_f32_e32 v182, v55, v182
	v_cvt_pk_bf16_f32 v181, v181, v182
	v_add_f32_e32 v183, 1.0, v183
	s_nop 0
	v_rcp_f32_e32 v183, v183
	v_mul_f32_e32 v184, 0xbfb8aa3b, v9
	v_exp_f32_e32 v184, v184
	v_mul_f32_e32 v183, v48, v183
	v_add_f32_e32 v184, 1.0, v184
	s_nop 0
	v_rcp_f32_e32 v184, v184
; __device__ __forceinline__ unsigned pk_bf16(float lo, float hi) { unsigned r; asm volatile("v_cvt_pk_bf16_f32 %0, %1, %2" : "=v"(r) : "v"(lo), "v"(hi)); return r; }
; __device__ __forceinline__ float sigm_f(float x) { return 1.0f / (1.0f + __expf(-x)); }
;     __device__ __forceinline__ void operator()(const f32x4 (&acc)[2][2][4][2], const Unit& u, int wr, int wc, int fr, int fq) const {
;     ...
;         const int row0 = u.pm * BM + wr * 64 + fr, col0 = u.pn * HALF + wc * 32 + 8 * fq;
; #pragma unroll
;         for (int ai = 0; ai < 2; ++ai)
; #pragma unroll
;             for (int m = 0; m < 4; ++m) { bf16_t* rowp = C + (size_t)(row0 + ai * HALF + m * 16) * DM + col0;
;                 float o[8];
; #pragma unroll
;                 for (int n = 0; n < 2; ++n) { const f32x4 za = acc[ai][0][m][n], zb = acc[ai][1][m][n];
; #pragma unroll
;                     for (int j = 0; j < 4; ++j) o[4 * n + j] = za[j] * sigm_f(zb[j]); }
;                 u32x4 w; w.x = pk_bf16(o[0], o[1]); w.y = pk_bf16(o[2], o[3]); w.z = pk_bf16(o[4], o[5]); w.w = pk_bf16(o[6], o[7]);
;                 *(u32x4*)rowp = w; }
	v_mul_f32_e32 v185, 0xbfb8aa3b, v10
	v_exp_f32_e32 v185, v185
	v_mul_f32_e32 v184, v49, v184
	v_cvt_pk_bf16_f32 v182, v183, v184
	v_add_f32_e32 v185, 1.0, v185
	s_nop 0
	v_rcp_f32_e32 v185, v185
	v_mul_f32_e32 v186, 0xbfb8aa3b, v11
	v_exp_f32_e32 v186, v186
	v_mul_f32_e32 v185, v50, v185
	v_add_f32_e32 v186, 1.0, v186
	s_nop 0
	v_rcp_f32_e32 v186, v186
	s_nop 0
	v_mul_f32_e32 v186, v51, v186
	v_cvt_pk_bf16_f32 v183, v185, v186
	global_store_dwordx4 v[160:161], v[180:183], off
	v_mul_f32_e32 v160, 0xbfb8aa3b, v4
	v_exp_f32_e32 v160, v160
	s_nop 0
	v_add_f32_e32 v160, 1.0, v160
	s_nop 0
	v_rcp_f32_e32 v160, v160
	v_mul_f32_e32 v161, 0xbfb8aa3b, v5
	v_exp_f32_e32 v161, v161
	v_mul_f32_e32 v160, v40, v160
	v_add_f32_e32 v161, 1.0, v161
	s_nop 0
	v_rcp_f32_e32 v161, v161
	v_mul_f32_e32 v180, 0xbfb8aa3b, v6
	v_exp_f32_e32 v180, v180
	v_mul_f32_e32 v161, v41, v161
	v_add_f32_e32 v180, 1.0, v180
	s_nop 0
	v_rcp_f32_e32 v180, v180
	s_nop 0
	v_mul_f32_e32 v182, v42, v180
	v_mul_f32_e32 v180, 0xbfb8aa3b, v7
	v_exp_f32_e32 v180, v180
	s_nop 0
	v_add_f32_e32 v180, 1.0, v180
	s_nop 0
	v_rcp_f32_e32 v180, v180
	s_nop 0
	v_mul_f32_e32 v183, v43, v180
	v_mul_f32_e32 v180, 0xbfb8aa3b, v0
	v_exp_f32_e32 v180, v180
	s_nop 0
	v_add_f32_e32 v180, 1.0, v180
	s_nop 0
	v_rcp_f32_e32 v180, v180
	s_nop 0
	v_mul_f32_e32 v184, v32, v180
	v_mul_f32_e32 v180, 0xbfb8aa3b, v1
	v_exp_f32_e32 v180, v180
	s_nop 0
	v_add_f32_e32 v180, 1.0, v180
	s_nop 0
	v_rcp_f32_e32 v180, v180
	s_nop 0
	v_mul_f32_e32 v185, v33, v180
	v_mul_f32_e32 v180, 0xbfb8aa3b, v2
	v_exp_f32_e32 v180, v180
	s_nop 0
	v_add_f32_e32 v180, 1.0, v180
	s_nop 0
	v_rcp_f32_e32 v180, v180
	s_nop 0
	v_mul_f32_e32 v186, v34, v180
	v_mul_f32_e32 v180, 0xbfb8aa3b, v3
	v_exp_f32_e32 v180, v180
	s_nop 0
	v_add_f32_e32 v180, 1.0, v180
	s_nop 0
	v_rcp_f32_e32 v180, v180
	s_nop 0
	v_mul_f32_e32 v187, v35, v180
	v_lshl_add_u64 v[180:181], v[158:159], 0, v[156:157]
	v_cvt_pk_bf16_f32 v156, v160, v161
	v_cvt_pk_bf16_f32 v157, v182, v183
	v_cvt_pk_bf16_f32 v158, v184, v185
	v_cvt_pk_bf16_f32 v159, v186, v187
	global_store_dwordx4 v[180:181], v[156:159], off
	s_nop 1
	s_nop 0
	v_rcp_f32_e32 v124, v124
	s_nop 0
	v_mul_f32_e32 v120, v120, v124
	v_mul_f32_e32 v124, 0xbfb8aa3b, v125
	v_exp_f32_e32 v124, v124
	s_nop 0
	v_add_f32_e32 v124, 1.0, v124
	s_nop 0
	v_rcp_f32_e32 v124, v124
	s_nop 0
	v_mul_f32_e32 v121, v121, v124
	v_mul_f32_e32 v124, 0xbfb8aa3b, v126
	v_exp_f32_e32 v124, v124
	s_nop 0
	v_add_f32_e32 v124, 1.0, v124
	s_nop 0
	v_rcp_f32_e32 v124, v124
	s_nop 0
	v_mul_f32_e32 v122, v122, v124
	v_mul_f32_e32 v124, 0xbfb8aa3b, v127
	v_exp_f32_e32 v124, v124
	s_nop 0
	v_add_f32_e32 v124, 1.0, v124
	s_nop 0
	v_rcp_f32_e32 v124, v124
	s_nop 0
	v_mul_f32_e32 v123, v123, v124
	s_nop 0
	v_rcp_f32_e32 v116, v116
	s_nop 0
	v_mul_f32_e32 v116, v112, v116
	v_mul_f32_e32 v112, 0xbfb8aa3b, v117
	v_exp_f32_e32 v112, v112
	s_nop 0
	v_add_f32_e32 v112, 1.0, v112
	s_nop 0
	v_rcp_f32_e32 v112, v112
	s_nop 0
	v_mul_f32_e32 v117, v113, v112
	v_mul_f32_e32 v112, 0xbfb8aa3b, v118
	v_exp_f32_e32 v112, v112
	s_nop 0
	v_add_f32_e32 v112, 1.0, v112
	s_nop 0
	v_rcp_f32_e32 v112, v112
	s_nop 0
	v_mul_f32_e32 v118, v114, v112
	v_mul_f32_e32 v112, 0xbfb8aa3b, v119
	v_exp_f32_e32 v112, v112
	s_nop 0
	v_add_f32_e32 v112, 1.0, v112
	s_nop 0
	v_rcp_f32_e32 v112, v112
	s_nop 0
	v_mul_f32_e32 v115, v115, v112
	v_cvt_pk_bf16_f32 v112, v120, v121
	v_cvt_pk_bf16_f32 v113, v122, v123
	v_cvt_pk_bf16_f32 v114, v116, v117
	v_add_co_u32_e32 v116, vcc, s79, v154
	v_cvt_pk_bf16_f32 v115, v118, v115
	s_nop 1
	v_addc_co_u32_e32 v117, vcc, 0, v155, vcc
	global_store_dwordx4 v[116:117], v[112:115], off
	s_nop 1
	s_nop 0
	v_rcp_f32_e32 v108, v108
	s_nop 0
	v_mul_f32_e32 v104, v104, v108
	v_mul_f32_e32 v108, 0xbfb8aa3b, v109
	v_exp_f32_e32 v108, v108
	s_nop 0
	v_add_f32_e32 v108, 1.0, v108
	s_nop 0
	v_rcp_f32_e32 v108, v108
	s_nop 0
	v_mul_f32_e32 v105, v105, v108
	v_mul_f32_e32 v108, 0xbfb8aa3b, v110
	v_exp_f32_e32 v108, v108
	s_nop 0
	v_add_f32_e32 v108, 1.0, v108
	s_nop 0
; __device__ __forceinline__ unsigned pk_bf16(float lo, float hi) { unsigned r; asm volatile("v_cvt_pk_bf16_f32 %0, %1, %2" : "=v"(r) : "v"(lo), "v"(hi)); return r; }
; __device__ __forceinline__ float sigm_f(float x) { return 1.0f / (1.0f + __expf(-x)); }
;     __device__ __forceinline__ void operator()(const f32x4 (&acc)[2][2][4][2], const Unit& u, int wr, int wc, int fr, int fq) const {
;     ...
;         const int row0 = u.pm * BM + wr * 64 + fr, col0 = u.pn * HALF + wc * 32 + 8 * fq;
; #pragma unroll
;         for (int ai = 0; ai < 2; ++ai)
; #pragma unroll
;             for (int m = 0; m < 4; ++m) { bf16_t* rowp = C + (size_t)(row0 + ai * HALF + m * 16) * DM + col0;
;                 float o[8];
; #pragma unroll
;                 for (int n = 0; n < 2; ++n) { const f32x4 za = acc[ai][0][m][n], zb = acc[ai][1][m][n];
; #pragma unroll
;                     for (int j = 0; j < 4; ++j) o[4 * n + j] = za[j] * sigm_f(zb[j]); }
;                 u32x4 w; w.x = pk_bf16(o[0], o[1]); w.y = pk_bf16(o[2], o[3]); w.z = pk_bf16(o[4], o[5]); w.w = pk_bf16(o[6], o[7]);
;                 *(u32x4*)rowp = w; }
	v_rcp_f32_e32 v108, v108
	s_nop 0
	v_mul_f32_e32 v106, v106, v108
	v_mul_f32_e32 v108, 0xbfb8aa3b, v111
	v_exp_f32_e32 v108, v108
	s_nop 0
	v_add_f32_e32 v108, 1.0, v108
	s_nop 0
	v_rcp_f32_e32 v108, v108
	s_nop 0
	v_mul_f32_e32 v107, v107, v108
	s_nop 0
	v_rcp_f32_e32 v100, v100
	s_nop 0
	v_mul_f32_e32 v100, v96, v100
	v_mul_f32_e32 v96, 0xbfb8aa3b, v101
	v_exp_f32_e32 v96, v96
	s_nop 0
	v_add_f32_e32 v96, 1.0, v96
	s_nop 0
	v_rcp_f32_e32 v96, v96
	s_nop 0
	v_mul_f32_e32 v101, v97, v96
	v_mul_f32_e32 v96, 0xbfb8aa3b, v102
	v_exp_f32_e32 v96, v96
	s_nop 0
	v_add_f32_e32 v96, 1.0, v96
	s_nop 0
	v_rcp_f32_e32 v96, v96
	s_nop 0
	v_mul_f32_e32 v102, v98, v96
	v_mul_f32_e32 v96, 0xbfb8aa3b, v103
	v_exp_f32_e32 v96, v96
	s_nop 0
	v_add_f32_e32 v96, 1.0, v96
	s_nop 0
	v_rcp_f32_e32 v96, v96
	s_nop 0
	v_mul_f32_e32 v99, v99, v96
	v_cvt_pk_bf16_f32 v96, v104, v105
	v_cvt_pk_bf16_f32 v97, v106, v107
	v_cvt_pk_bf16_f32 v98, v100, v101
	v_add_co_u32_e32 v100, vcc, s5, v154
	v_cvt_pk_bf16_f32 v99, v102, v99
	s_mov_b32 s5, 0xa0000
	s_nop 0
	v_addc_co_u32_e32 v101, vcc, 0, v155, vcc
	global_store_dwordx4 v[100:101], v[96:99], off
	s_nop 1
	s_nop 0
	v_rcp_f32_e32 v92, v92
	s_nop 0
	v_mul_f32_e32 v88, v88, v92
	v_mul_f32_e32 v92, 0xbfb8aa3b, v93
	v_exp_f32_e32 v92, v92
	s_nop 0
	v_add_f32_e32 v92, 1.0, v92
	s_nop 0
	v_rcp_f32_e32 v92, v92
	s_nop 0
	v_mul_f32_e32 v89, v89, v92
	v_mul_f32_e32 v92, 0xbfb8aa3b, v94
	v_exp_f32_e32 v92, v92
	s_nop 0
	v_add_f32_e32 v92, 1.0, v92
	s_nop 0
	v_rcp_f32_e32 v92, v92
	s_nop 0
	v_mul_f32_e32 v90, v90, v92
	v_mul_f32_e32 v92, 0xbfb8aa3b, v95
	v_exp_f32_e32 v92, v92
	s_nop 0
	v_add_f32_e32 v92, 1.0, v92
	s_nop 0
	v_rcp_f32_e32 v92, v92
	s_nop 0
	v_mul_f32_e32 v91, v91, v92
	s_nop 0
	v_rcp_f32_e32 v84, v84
	s_nop 0
	v_mul_f32_e32 v84, v80, v84
	v_mul_f32_e32 v80, 0xbfb8aa3b, v85
	v_exp_f32_e32 v80, v80
	s_nop 0
	v_add_f32_e32 v80, 1.0, v80
	s_nop 0
	v_rcp_f32_e32 v80, v80
	s_nop 0
	v_mul_f32_e32 v85, v81, v80
	v_mul_f32_e32 v80, 0xbfb8aa3b, v86
	v_exp_f32_e32 v80, v80
	s_nop 0
	v_add_f32_e32 v80, 1.0, v80
	s_nop 0
	v_rcp_f32_e32 v80, v80
	s_nop 0
	v_mul_f32_e32 v86, v82, v80
	v_mul_f32_e32 v80, 0xbfb8aa3b, v87
	v_exp_f32_e32 v80, v80
	s_nop 0
	v_add_f32_e32 v80, 1.0, v80
	s_nop 0
	v_rcp_f32_e32 v80, v80
	s_nop 0
	v_mul_f32_e32 v83, v83, v80
	v_cvt_pk_bf16_f32 v80, v88, v89
	v_cvt_pk_bf16_f32 v81, v90, v91
	v_cvt_pk_bf16_f32 v82, v84, v85
	v_add_co_u32_e32 v84, vcc, s5, v154
	v_cvt_pk_bf16_f32 v83, v86, v83
	s_nop 1
	v_addc_co_u32_e32 v85, vcc, 0, v155, vcc
	global_store_dwordx4 v[84:85], v[80:83], off
	s_nop 1
	s_nop 0
	v_rcp_f32_e32 v76, v76
	s_nop 0
	v_mul_f32_e32 v72, v72, v76
	v_mul_f32_e32 v76, 0xbfb8aa3b, v77
	v_exp_f32_e32 v76, v76
	s_nop 0
	v_add_f32_e32 v76, 1.0, v76
	s_nop 0
	v_rcp_f32_e32 v76, v76
	s_nop 0
	v_mul_f32_e32 v73, v73, v76
	v_mul_f32_e32 v76, 0xbfb8aa3b, v78
	v_exp_f32_e32 v76, v76
	s_nop 0
	v_add_f32_e32 v76, 1.0, v76
	s_nop 0
	v_rcp_f32_e32 v76, v76
	s_nop 0
	v_mul_f32_e32 v74, v74, v76
	v_mul_f32_e32 v76, 0xbfb8aa3b, v79
	v_exp_f32_e32 v76, v76
	s_nop 0
	v_add_f32_e32 v76, 1.0, v76
	s_nop 0
	v_rcp_f32_e32 v76, v76
	s_nop 0
	v_mul_f32_e32 v75, v75, v76
	s_nop 0
	v_rcp_f32_e32 v28, v28
	s_nop 0
	v_mul_f32_e32 v28, v16, v28
	v_mul_f32_e32 v16, 0xbfb8aa3b, v29
	v_exp_f32_e32 v16, v16
	s_nop 0
	v_add_f32_e32 v16, 1.0, v16
	s_nop 0
	v_rcp_f32_e32 v16, v16
	s_nop 0
	v_mul_f32_e32 v29, v17, v16
	v_mul_f32_e32 v16, 0xbfb8aa3b, v30
	v_exp_f32_e32 v16, v16
	s_nop 0
	v_add_f32_e32 v16, 1.0, v16
	s_nop 0
	v_rcp_f32_e32 v16, v16
	s_nop 0
	v_mul_f32_e32 v30, v18, v16
	v_mul_f32_e32 v16, 0xbfb8aa3b, v31
	v_exp_f32_e32 v16, v16
	s_nop 0
	v_add_f32_e32 v16, 1.0, v16
	s_nop 0
	v_rcp_f32_e32 v16, v16
	s_nop 0
	v_mul_f32_e32 v19, v19, v16
	v_cvt_pk_bf16_f32 v16, v72, v73
	v_cvt_pk_bf16_f32 v17, v74, v75
	v_cvt_pk_bf16_f32 v18, v28, v29
	v_add_co_u32_e32 v28, vcc, 0xb0000, v154
	v_cvt_pk_bf16_f32 v19, v30, v19
	s_nop 1
	v_addc_co_u32_e32 v29, vcc, 0, v155, vcc
	global_store_dwordx4 v[28:29], v[16:19], off
	s_cbranch_execz .LBB0_54

; #define LAS __attribute__((address_space(3)))
; __device__ __forceinline__ bf16_t f2bf(float f) { return (bf16_t)(pk_bf16(f, 0.f) & 0xffffu); }
; __device__ __forceinline__ float ret_lg2(int h) { return log2f(1.0f - exp2f(-5.0f - (float)h)); }
; __device__ __forceinline__ void ret_out_unit(int b, int h, int c, LAS unsigned char* lds, const bf16_t* PROJ, const float* KV, bf16_t* H, int tid) {
;     ...
;     const float lg2 = ret_lg2(h);
;     const size_t R0 = (size_t)b * SEQ + (size_t)c * 128;
; #pragma unroll
;     for (int r = 0; r < 4; ++r) { const int idx = tid + 512 * r, tok = idx & 127, seg = idx >> 7;
;         const bf16_t* rp = PROJ + (R0 + tok) * EIN + h * 128 + seg * 8;
;         const u32x4 kv = *(const u32x4*)(rp + 1024), vv = *(const u32x4*)(rp + 2048);
;         *(LAS u32x4*)(Ks + tok * 272 + seg * 16) = kv;
; #pragma unroll
;         for (int i = 0; i < 4; ++i) {
;             *(LAS bf16_t*)(VT + (seg * 8 + 2 * i) * 272 + tok * 2) = (bf16_t)(vv[i] & 0xffffu);
;             *(LAS bf16_t*)(VT + (seg * 8 + 2 * i + 1) * 272 + tok * 2) = (bf16_t)(vv[i] >> 16); } }
;     const float* Sp = KV + ((size_t)((b * 8 + h) * 32 + c)) * 16384;
; #pragma unroll
;     for (int r = 0; r < 8; ++r) { const int idx = tid + 512 * r, d = idx & 127, es = idx >> 7;
;         const f32x4 s4 = *(const f32x4*)(Sp + (size_t)d * 128 + 4 * es);
; #pragma unroll
;         for (int i = 0; i < 4; ++i) *(LAS bf16_t*)(ST + (4 * es + i) * 272 + d * 2) = f2bf(s4[i]); }
;     __syncthreads();
.LBB0_418:
	s_bfe_u32 s22, s3, 0x30005
	v_cvt_f32_ubyte0_e32 v0, s22
	v_sub_f32_e32 v0, 0xc0a00000, v0
	v_cmp_gt_f32_e32 vcc, s34, v0
	s_and_b32 s13, s3, 31
	s_ashr_i32 s18, s3, 8
	v_cndmask_b32_e32 v1, 0, v168, vcc
	v_add_f32_e32 v0, v0, v1
	v_exp_f32_e32 v0, v0
	s_and_b64 s[20:21], vcc, exec
	s_cselect_b32 s19, 0xffffffc0, 0
	s_lshl_b32 s20, s13, 7
	v_ldexp_f32 v0, v0, s19
	s_ashr_i32 s19, s18, 31
	s_lshl_b64 s[18:19], s[18:19], 12
	s_or_b32 s18, s18, s20
	v_sub_f32_e32 v16, 1.0, v0
	v_or_b32_e32 v0, s18, v80
	v_mov_b64_e32 v[4:5], s[16:17]
	v_mad_u64_u32 v[0:1], s[20:21], v0, s35, v[4:5]
	v_mad_i32_i24 v1, s19, v169, v1
	s_lshl_b32 s24, s22, 8
	v_lshl_add_u64 v[6:7], v[0:1], 0, s[24:25]
	v_lshl_add_u64 v[8:9], v[82:83], 1, v[6:7]
	global_load_dwordx4 v[0:3], v[8:9], off offset:2048
	s_and_b32 s20, s3, 0xffffff00
	s_lshl_b32 s21, s22, 5
	s_or_b32 s20, s21, s20
	s_or_b32 s20, s20, s13
	s_ashr_i32 s21, s20, 31
	s_lshl_b64 s[20:21], s[20:21], 16
	v_lshl_add_u64 v[114:115], s[18:19], 0, v[108:109]
	v_lshlrev_b32_e32 v128, 1, v110
	v_add_u32_e32 v24, v111, v110
	s_waitcnt vmcnt(0)
	ds_write_b128 v160, v[0:3]
	v_add_co_u32_e32 v0, vcc, s33, v8
	s_nop 1
	v_addc_co_u32_e32 v1, vcc, 0, v9, vcc
	global_load_dwordx4 v[0:3], v[0:1], off
	v_lshl_add_u64 v[8:9], v[84:85], 1, v[6:7]
	s_waitcnt vmcnt(0)
	ds_write_b16 v161, v0 offset:34816
	ds_write_b16_d16_hi v161, v0 offset:35088
	ds_write_b16 v161, v1 offset:35360
	ds_write_b16_d16_hi v161, v1 offset:35632
	ds_write_b16 v161, v2 offset:35904
	ds_write_b16_d16_hi v161, v2 offset:36176
	ds_write_b16 v161, v3 offset:36448
	ds_write_b16_d16_hi v161, v3 offset:36720
	global_load_dwordx4 v[0:3], v[8:9], off offset:2048
	s_waitcnt vmcnt(0)
	ds_write_b128 v180, v[0:3]
	v_add_co_u32_e32 v0, vcc, s33, v8
	s_nop 1
	v_addc_co_u32_e32 v1, vcc, 0, v9, vcc
	global_load_dwordx4 v[0:3], v[0:1], off
	v_lshl_add_u64 v[8:9], v[86:87], 1, v[6:7]
	v_lshl_add_u64 v[6:7], v[88:89], 1, v[6:7]
	s_waitcnt vmcnt(0)
	ds_write_b16 v181, v0 offset:34816
	ds_write_b16_d16_hi v181, v0 offset:35088
	ds_write_b16 v181, v1 offset:35360
	ds_write_b16_d16_hi v181, v1 offset:35632
	ds_write_b16 v181, v2 offset:35904
	ds_write_b16_d16_hi v181, v2 offset:36176
	ds_write_b16 v181, v3 offset:36448
	ds_write_b16_d16_hi v181, v3 offset:36720
	global_load_dwordx4 v[0:3], v[8:9], off offset:2048
	s_waitcnt vmcnt(0)
	ds_write_b128 v182, v[0:3]
	v_add_co_u32_e32 v0, vcc, s33, v8
	s_nop 1
	v_addc_co_u32_e32 v1, vcc, 0, v9, vcc
	global_load_dwordx4 v[0:3], v[0:1], off
	s_waitcnt vmcnt(0)
	ds_write_b16 v183, v0 offset:34816
	ds_write_b16_d16_hi v183, v0 offset:35088
	ds_write_b16 v183, v1 offset:35360
	ds_write_b16_d16_hi v183, v1 offset:35632
	ds_write_b16 v183, v2 offset:35904
	ds_write_b16_d16_hi v183, v2 offset:36176
	ds_write_b16 v183, v3 offset:36448
	ds_write_b16_d16_hi v183, v3 offset:36720
	global_load_dwordx4 v[0:3], v[6:7], off offset:2048
	s_waitcnt vmcnt(0)
	ds_write_b128 v184, v[0:3]
	v_add_co_u32_e32 v0, vcc, s33, v6
	s_nop 1
	v_addc_co_u32_e32 v1, vcc, 0, v7, vcc
	global_load_dwordx4 v[0:3], v[0:1], off
	v_lshl_add_u64 v[6:7], v[90:91], 0, s[20:21]
	v_cmp_gt_f32_e32 vcc, s23, v16
	s_and_b64 s[18:19], vcc, exec
	s_cselect_b32 s13, 32, 0
	v_ldexp_f32 v16, v16, s13
	v_log_f32_e32 v16, v16
	v_cndmask_b32_e32 v17, 0, v170, vcc
	s_waitcnt vmcnt(0)
	ds_write_b16 v185, v0 offset:34816
	ds_write_b16_d16_hi v185, v0 offset:35088
	ds_write_b16 v185, v1 offset:35360
	ds_write_b16_d16_hi v185, v1 offset:35632
	ds_write_b16 v185, v2 offset:35904
	ds_write_b16_d16_hi v185, v2 offset:36176
	ds_write_b16 v185, v3 offset:36448
	ds_write_b16_d16_hi v185, v3 offset:36720
	v_lshl_add_u64 v[0:1], v[92:93], 2, v[6:7]
	global_load_dwordx4 v[0:3], v[0:1], off
	s_waitcnt vmcnt(0)
	v_cvt_pk_bf16_f32 v0, v0, v129
	ds_write_b16 v186, v0
	v_cvt_pk_bf16_f32 v0, v1, v129
	ds_write_b16 v186, v0 offset:272
	v_cvt_pk_bf16_f32 v0, v2, v129
	ds_write_b16 v186, v0 offset:544
	v_cvt_pk_bf16_f32 v0, v3, v129
	ds_write_b16 v187, v0
	v_lshl_add_u64 v[0:1], v[94:95], 2, v[6:7]
	global_load_dwordx4 v[0:3], v[0:1], off
	s_waitcnt vmcnt(0)
	v_cvt_pk_bf16_f32 v0, v0, v129
	ds_write_b16 v188, v0
	v_cvt_pk_bf16_f32 v0, v1, v129
	ds_write_b16 v188, v0 offset:272
	v_cvt_pk_bf16_f32 v0, v2, v129
	ds_write_b16 v188, v0 offset:544
	v_cvt_pk_bf16_f32 v0, v3, v129
	ds_write_b16 v189, v0
	v_lshl_add_u64 v[0:1], v[96:97], 2, v[6:7]
	global_load_dwordx4 v[0:3], v[0:1], off
	s_waitcnt vmcnt(0)
	v_cvt_pk_bf16_f32 v0, v0, v129
	ds_write_b16 v190, v0
	v_cvt_pk_bf16_f32 v0, v1, v129
	ds_write_b16 v190, v0 offset:272
	v_cvt_pk_bf16_f32 v0, v2, v129
	ds_write_b16 v190, v0 offset:544
	v_cvt_pk_bf16_f32 v0, v3, v129
	ds_write_b16 v191, v0
	v_lshl_add_u64 v[0:1], v[98:99], 2, v[6:7]
	global_load_dwordx4 v[0:3], v[0:1], off
	s_waitcnt vmcnt(0)
	v_cvt_pk_bf16_f32 v0, v0, v129
	ds_write_b16 v192, v0
	v_cvt_pk_bf16_f32 v0, v1, v129
	ds_write_b16 v192, v0 offset:272
	v_cvt_pk_bf16_f32 v0, v2, v129
	ds_write_b16 v192, v0 offset:544
	v_cvt_pk_bf16_f32 v0, v3, v129
	ds_write_b16 v193, v0
	v_lshl_add_u64 v[0:1], v[100:101], 2, v[6:7]
	global_load_dwordx4 v[0:3], v[0:1], off
	s_waitcnt vmcnt(0)
	v_cvt_pk_bf16_f32 v0, v0, v129
	ds_write_b16 v194, v0
	v_cvt_pk_bf16_f32 v0, v1, v129
	ds_write_b16 v194, v0 offset:272
	v_cvt_pk_bf16_f32 v0, v2, v129
	ds_write_b16 v194, v0 offset:544
	v_cvt_pk_bf16_f32 v0, v3, v129
	ds_write_b16 v195, v0
	v_lshl_add_u64 v[0:1], v[102:103], 2, v[6:7]
	global_load_dwordx4 v[0:3], v[0:1], off
	s_waitcnt vmcnt(0)
	v_cvt_pk_bf16_f32 v0, v0, v129
	ds_write_b16 v196, v0
	v_cvt_pk_bf16_f32 v0, v1, v129
	ds_write_b16 v196, v0 offset:272
	v_cvt_pk_bf16_f32 v0, v2, v129
	ds_write_b16 v196, v0 offset:544
	v_cvt_pk_bf16_f32 v0, v3, v129
	ds_write_b16 v197, v0
	v_lshl_add_u64 v[0:1], v[104:105], 2, v[6:7]
	global_load_dwordx4 v[0:3], v[0:1], off
	s_waitcnt vmcnt(0)
	v_cvt_pk_bf16_f32 v0, v0, v129
	ds_write_b16 v198, v0
	v_cvt_pk_bf16_f32 v0, v1, v129
	ds_write_b16 v198, v0 offset:272
	v_cvt_pk_bf16_f32 v0, v2, v129
	ds_write_b16 v198, v0 offset:544
	v_cvt_pk_bf16_f32 v0, v3, v129
	ds_write_b16 v199, v0
	v_lshl_add_u64 v[0:1], v[106:107], 2, v[6:7]
	global_load_dwordx4 v[0:3], v[0:1], off
	s_waitcnt vmcnt(0)
	v_cvt_pk_bf16_f32 v0, v0, v129
	ds_write_b16 v200, v0
	v_cvt_pk_bf16_f32 v0, v1, v129
	ds_write_b16 v200, v0 offset:272
	v_cvt_pk_bf16_f32 v0, v2, v129
	ds_write_b16 v200, v0 offset:544
	v_cvt_pk_bf16_f32 v0, v3, v129
	ds_write_b16 v201, v0
	v_mad_u64_u32 v[0:1], s[18:19], v114, s35, v[4:5]
	v_mad_i32_i24 v1, v115, s35, v1
	v_lshl_add_u64 v[116:117], v[0:1], 0, s[24:25]
	v_lshl_add_u64 v[0:1], v[116:117], 0, v[128:129]
	s_waitcnt lgkmcnt(0)
	s_barrier
; #define LAS __attribute__((address_space(3)))
; __device__ __forceinline__ unsigned pk_bf16(float lo, float hi) { unsigned r; asm volatile("v_cvt_pk_bf16_f32 %0, %1, %2" : "=v"(r) : "v"(lo), "v"(hi)); return r; }
; __device__ __forceinline__ f32x4 mfma16(bf16x8 a, bf16x8 b, f32x4 c) { return __builtin_amdgcn_mfma_f32_16x16x32_bf16(a, b, c, 0, 0, 0); }
; __device__ __forceinline__ void ret_out_unit(int b, int h, int c, LAS unsigned char* lds, const bf16_t* PROJ, const float* KV, bf16_t* H, int tid) {
;     ...
;     const int i = 16 * wave + fr;
;     const size_t qrow = R0 + i;
;     bf16x8 qf[4];
; #pragma unroll
;     for (int kk = 0; kk < 4; ++kk) qf[kk] = *(const bf16x8*)(PROJ + qrow * EIN + h * 128 + 32 * kk + 8 * fq);
; #pragma unroll
;     for (int cb = 0; cb < 8; ++cb) { f32x4 acc = {0.f, 0.f, 0.f, 0.f};
; #pragma unroll
;         for (int kk = 0; kk < 4; ++kk) { const bf16x8 kf = *(const LAS bf16x8*)(Ks + (16 * cb + fr) * 272 + (32 * kk + 8 * fq) * 2); acc = mfma16(kf, qf[kk], acc); }
;         float v[4];
; #pragma unroll
;         for (int t = 0; t < 4; ++t) { const int dl = i - (16 * cb + 4 * fq + t); v[t] = dl >= 0 ? acc[t] * 0.08838834764831845f * exp2f(lg2 * (float)dl) : 0.f; }
;         u32x2 w; w.x = pk_bf16(v[0], v[1]); w.y = pk_bf16(v[2], v[3]);
;         *(LAS u32x2*)(SC + i * 272 + (16 * cb + 4 * fq) * 2) = w; }
	global_load_dwordx4 v[12:15], v[0:1], off
	global_load_dwordx4 v[8:11], v[0:1], off offset:64
	global_load_dwordx4 v[4:7], v[0:1], off offset:128
	s_nop 0
	global_load_dwordx4 v[0:3], v[0:1], off offset:192
	v_sub_f32_e32 v113, v16, v17
	ds_read_b128 v[16:19], v118
	ds_read_b128 v[20:23], v118 offset:64
	v_add_u32_e32 v128, v111, v81
	s_add_u32 s18, s6, s24
	s_addc_u32 s19, s7, 0
	s_add_i32 s3, s3, s2
	s_cmpk_gt_i32 s3, 0x1ff
	s_waitcnt vmcnt(3) lgkmcnt(1)
	v_mfma_f32_16x16x32_bf16 v[16:19], v[16:19], v[12:15], 0
	s_waitcnt vmcnt(2) lgkmcnt(0)
	v_mfma_f32_16x16x32_bf16 v[16:19], v[20:23], v[8:11], v[16:19]
	ds_read_b128 v[20:23], v118 offset:128
	s_waitcnt vmcnt(1) lgkmcnt(0)
	v_mfma_f32_16x16x32_bf16 v[16:19], v[20:23], v[4:7], v[16:19]
	ds_read_b128 v[20:23], v118 offset:192
	s_waitcnt vmcnt(0) lgkmcnt(0)
	v_mfma_f32_16x16x32_bf16 v[16:19], v[20:23], v[0:3], v[16:19]
	v_mul_f32_e32 v20, v113, v119
	v_cmp_gt_f32_e32 vcc, s34, v20
	s_nop 5
	v_mul_f32_e32 v16, 0x3db504f3, v16
	v_cndmask_b32_e32 v20, 0, v168, vcc
	v_fmac_f32_e32 v20, v113, v119
	v_exp_f32_e32 v20, v20
	v_cndmask_b32_e32 v21, 0, v171, vcc
	v_mul_f32_e32 v17, 0x3db504f3, v17
	v_mul_f32_e32 v18, 0x3db504f3, v18
	v_ldexp_f32 v20, v20, v21
	v_mul_f32_e32 v16, v20, v16
	v_mul_f32_e32 v20, v113, v120
	v_cmp_gt_f32_e32 vcc, s34, v20
	v_mul_f32_e32 v19, 0x3db504f3, v19
	v_cndmask_b32_e64 v16, 0, v16, s[38:39]
	v_cndmask_b32_e32 v20, 0, v168, vcc
	v_fmac_f32_e32 v20, v113, v120
	v_exp_f32_e32 v20, v20
	v_cndmask_b32_e32 v21, 0, v171, vcc
	v_ldexp_f32 v20, v20, v21
	v_mul_f32_e32 v17, v20, v17
	v_mul_f32_e32 v20, v113, v121
	v_cmp_gt_f32_e32 vcc, s34, v20
	v_cndmask_b32_e64 v17, 0, v17, s[40:41]
	v_cvt_pk_bf16_f32 v16, v16, v17
	s_nop 0
	v_cndmask_b32_e32 v20, 0, v168, vcc
	v_fmac_f32_e32 v20, v113, v121
	v_exp_f32_e32 v20, v20
	v_cndmask_b32_e32 v21, 0, v171, vcc
	v_ldexp_f32 v20, v20, v21
	v_mul_f32_e32 v18, v20, v18
	v_mul_f32_e32 v20, v113, v122
	v_cmp_gt_f32_e32 vcc, s34, v20
	v_cndmask_b32_e64 v18, 0, v18, s[42:43]
	s_nop 0
	v_cndmask_b32_e32 v20, 0, v168, vcc
	v_fmac_f32_e32 v20, v113, v122
	v_exp_f32_e32 v20, v20
	v_cndmask_b32_e32 v21, 0, v171, vcc
	v_ldexp_f32 v20, v20, v21
	v_mul_f32_e32 v19, v20, v19
	v_cndmask_b32_e64 v19, 0, v19, s[44:45]
	v_cvt_pk_bf16_f32 v17, v18, v19
	ds_write_b64 v24, v[16:17]
	ds_read_b128 v[16:19], v118 offset:4352
	ds_read_b128 v[20:23], v118 offset:4416
	s_waitcnt lgkmcnt(1)
	v_mfma_f32_16x16x32_bf16 v[16:19], v[16:19], v[12:15], 0
	s_waitcnt lgkmcnt(0)
	v_mfma_f32_16x16x32_bf16 v[16:19], v[20:23], v[8:11], v[16:19]
	ds_read_b128 v[20:23], v118 offset:4480
	s_waitcnt lgkmcnt(0)
	v_mfma_f32_16x16x32_bf16 v[16:19], v[20:23], v[4:7], v[16:19]
	ds_read_b128 v[20:23], v118 offset:4544
	s_waitcnt lgkmcnt(0)
	v_mfma_f32_16x16x32_bf16 v[16:19], v[20:23], v[0:3], v[16:19]
	v_mul_f32_e32 v20, v113, v123
	v_cmp_gt_f32_e32 vcc, s34, v20
	s_nop 5
	v_mul_f32_e32 v16, 0x3db504f3, v16
	v_cndmask_b32_e32 v20, 0, v168, vcc
	v_fmac_f32_e32 v20, v113, v123
	v_exp_f32_e32 v20, v20
	v_cndmask_b32_e32 v21, 0, v171, vcc
	v_mul_f32_e32 v17, 0x3db504f3, v17
	v_mul_f32_e32 v18, 0x3db504f3, v18
	v_ldexp_f32 v20, v20, v21
	v_mul_f32_e32 v16, v20, v16
	v_mul_f32_e32 v20, v113, v124
	v_cmp_gt_f32_e32 vcc, s34, v20
	v_mul_f32_e32 v19, 0x3db504f3, v19
	v_cndmask_b32_e64 v16, 0, v16, s[46:47]
	v_cndmask_b32_e32 v20, 0, v168, vcc
	v_fmac_f32_e32 v20, v113, v124
	v_exp_f32_e32 v20, v20
	v_cndmask_b32_e32 v21, 0, v171, vcc
	v_ldexp_f32 v20, v20, v21
	v_mul_f32_e32 v17, v20, v17
	v_mul_f32_e32 v20, v113, v125
	v_cmp_gt_f32_e32 vcc, s34, v20
	v_cndmask_b32_e64 v17, 0, v17, s[48:49]
	v_cvt_pk_bf16_f32 v16, v16, v17
	s_nop 0
	v_cndmask_b32_e32 v20, 0, v168, vcc
	v_fmac_f32_e32 v20, v113, v125
	v_exp_f32_e32 v20, v20
	v_cndmask_b32_e32 v21, 0, v171, vcc
	v_ldexp_f32 v20, v20, v21
	v_mul_f32_e32 v18, v20, v18
	v_mul_f32_e32 v20, v113, v126
	v_cmp_gt_f32_e32 vcc, s34, v20
	v_cndmask_b32_e64 v18, 0, v18, s[50:51]
	s_nop 0
	v_cndmask_b32_e32 v20, 0, v168, vcc
	v_fmac_f32_e32 v20, v113, v126
	v_exp_f32_e32 v20, v20
	v_cndmask_b32_e32 v21, 0, v171, vcc
	v_ldexp_f32 v20, v20, v21
	v_mul_f32_e32 v19, v20, v19
	v_cndmask_b32_e64 v19, 0, v19, s[52:53]
	v_cvt_pk_bf16_f32 v17, v18, v19
	ds_write_b64 v24, v[16:17] offset:32
	ds_read_b128 v[16:19], v118 offset:8704
	ds_read_b128 v[20:23], v118 offset:8768
	s_waitcnt lgkmcnt(1)
	v_mfma_f32_16x16x32_bf16 v[16:19], v[16:19], v[12:15], 0
	s_waitcnt lgkmcnt(0)
	v_mfma_f32_16x16x32_bf16 v[16:19], v[20:23], v[8:11], v[16:19]
	ds_read_b128 v[20:23], v118 offset:8832
	s_waitcnt lgkmcnt(0)
	v_mfma_f32_16x16x32_bf16 v[16:19], v[20:23], v[4:7], v[16:19]
	ds_read_b128 v[20:23], v118 offset:8896
	s_waitcnt lgkmcnt(0)
	v_mfma_f32_16x16x32_bf16 v[16:19], v[20:23], v[0:3], v[16:19]
	v_mul_f32_e32 v20, v113, v127
	v_cmp_gt_f32_e32 vcc, s34, v20
	s_nop 5
	v_mul_f32_e32 v16, 0x3db504f3, v16
	v_cndmask_b32_e32 v20, 0, v168, vcc
	v_fmac_f32_e32 v20, v113, v127
	v_exp_f32_e32 v20, v20
	v_cndmask_b32_e32 v21, 0, v171, vcc
	v_mul_f32_e32 v17, 0x3db504f3, v17
	v_mul_f32_e32 v18, 0x3db504f3, v18
	v_ldexp_f32 v20, v20, v21
	v_mul_f32_e32 v16, v20, v16
	v_mul_f32_e32 v20, v113, v130
	v_cmp_gt_f32_e32 vcc, s34, v20
	v_mul_f32_e32 v19, 0x3db504f3, v19
	v_cndmask_b32_e64 v16, 0, v16, s[54:55]
	v_cndmask_b32_e32 v20, 0, v168, vcc
	v_fmac_f32_e32 v20, v113, v130
	v_exp_f32_e32 v20, v20
	v_cndmask_b32_e32 v21, 0, v171, vcc
	v_ldexp_f32 v20, v20, v21
	v_mul_f32_e32 v17, v20, v17
	v_mul_f32_e32 v20, v113, v133
	v_cmp_gt_f32_e32 vcc, s34, v20
	v_cndmask_b32_e64 v17, 0, v17, s[56:57]
	v_cvt_pk_bf16_f32 v16, v16, v17
	s_nop 0
	v_cndmask_b32_e32 v20, 0, v168, vcc
	v_fmac_f32_e32 v20, v113, v133
	v_exp_f32_e32 v20, v20
	v_cndmask_b32_e32 v21, 0, v171, vcc
	v_ldexp_f32 v20, v20, v21
	v_mul_f32_e32 v18, v20, v18
	v_mul_f32_e32 v20, v113, v134
	v_cmp_gt_f32_e32 vcc, s34, v20
	v_cndmask_b32_e64 v18, 0, v18, s[58:59]
	s_nop 0
	v_cndmask_b32_e32 v20, 0, v168, vcc
	v_fmac_f32_e32 v20, v113, v134
	v_exp_f32_e32 v20, v20
	v_cndmask_b32_e32 v21, 0, v171, vcc
	v_ldexp_f32 v20, v20, v21
	v_mul_f32_e32 v19, v20, v19
	v_cndmask_b32_e64 v19, 0, v19, s[60:61]
	v_cvt_pk_bf16_f32 v17, v18, v19
	ds_write_b64 v24, v[16:17] offset:64
	ds_read_b128 v[16:19], v118 offset:13056
	ds_read_b128 v[20:23], v118 offset:13120
	s_waitcnt lgkmcnt(1)
; #define LAS __attribute__((address_space(3)))
; __device__ __forceinline__ unsigned pk_bf16(float lo, float hi) { unsigned r; asm volatile("v_cvt_pk_bf16_f32 %0, %1, %2" : "=v"(r) : "v"(lo), "v"(hi)); return r; }
; __device__ __forceinline__ f32x4 mfma16(bf16x8 a, bf16x8 b, f32x4 c) { return __builtin_amdgcn_mfma_f32_16x16x32_bf16(a, b, c, 0, 0, 0); }
; __device__ __forceinline__ void ret_out_unit(int b, int h, int c, LAS unsigned char* lds, const bf16_t* PROJ, const float* KV, bf16_t* H, int tid) {
;     ...
;     for (int cb = 0; cb < 8; ++cb) { f32x4 acc = {0.f, 0.f, 0.f, 0.f};
; #pragma unroll
;         for (int kk = 0; kk < 4; ++kk) { const bf16x8 kf = *(const LAS bf16x8*)(Ks + (16 * cb + fr) * 272 + (32 * kk + 8 * fq) * 2); acc = mfma16(kf, qf[kk], acc); }
;         float v[4];
; #pragma unroll
;         for (int t = 0; t < 4; ++t) { const int dl = i - (16 * cb + 4 * fq + t); v[t] = dl >= 0 ? acc[t] * 0.08838834764831845f * exp2f(lg2 * (float)dl) : 0.f; }
;         u32x2 w; w.x = pk_bf16(v[0], v[1]); w.y = pk_bf16(v[2], v[3]);
;         *(LAS u32x2*)(SC + i * 272 + (16 * cb + 4 * fq) * 2) = w; }
	v_mfma_f32_16x16x32_bf16 v[16:19], v[16:19], v[12:15], 0
	s_waitcnt lgkmcnt(0)
	v_mfma_f32_16x16x32_bf16 v[16:19], v[20:23], v[8:11], v[16:19]
	ds_read_b128 v[20:23], v118 offset:13184
	s_waitcnt lgkmcnt(0)
	v_mfma_f32_16x16x32_bf16 v[16:19], v[20:23], v[4:7], v[16:19]
	ds_read_b128 v[20:23], v118 offset:13248
	s_waitcnt lgkmcnt(0)
	v_mfma_f32_16x16x32_bf16 v[16:19], v[20:23], v[0:3], v[16:19]
	v_mul_f32_e32 v20, v113, v135
	v_cmp_gt_f32_e32 vcc, s34, v20
	s_nop 5
	v_mul_f32_e32 v16, 0x3db504f3, v16
	v_cndmask_b32_e32 v20, 0, v168, vcc
	v_fmac_f32_e32 v20, v113, v135
	v_exp_f32_e32 v20, v20
	v_cndmask_b32_e32 v21, 0, v171, vcc
	v_mul_f32_e32 v17, 0x3db504f3, v17
	v_mul_f32_e32 v18, 0x3db504f3, v18
	v_ldexp_f32 v20, v20, v21
	v_mul_f32_e32 v16, v20, v16
	v_mul_f32_e32 v20, v113, v136
	v_cmp_gt_f32_e32 vcc, s34, v20
	v_mul_f32_e32 v19, 0x3db504f3, v19
	v_cndmask_b32_e64 v16, 0, v16, s[62:63]
	v_cndmask_b32_e32 v20, 0, v168, vcc
	v_fmac_f32_e32 v20, v113, v136
	v_exp_f32_e32 v20, v20
	v_cndmask_b32_e32 v21, 0, v171, vcc
	v_ldexp_f32 v20, v20, v21
	v_mul_f32_e32 v17, v20, v17
	v_mul_f32_e32 v20, v113, v137
	v_cmp_gt_f32_e32 vcc, s34, v20
	v_cndmask_b32_e64 v17, 0, v17, s[64:65]
	v_cvt_pk_bf16_f32 v16, v16, v17
	s_nop 0
	v_cndmask_b32_e32 v20, 0, v168, vcc
	v_fmac_f32_e32 v20, v113, v137
	v_exp_f32_e32 v20, v20
	v_cndmask_b32_e32 v21, 0, v171, vcc
	v_ldexp_f32 v20, v20, v21
	v_mul_f32_e32 v18, v20, v18
	v_mul_f32_e32 v20, v113, v138
	v_cmp_gt_f32_e32 vcc, s34, v20
	v_cndmask_b32_e64 v18, 0, v18, s[66:67]
	s_nop 0
	v_cndmask_b32_e32 v20, 0, v168, vcc
	v_fmac_f32_e32 v20, v113, v138
	v_exp_f32_e32 v20, v20
	v_cndmask_b32_e32 v21, 0, v171, vcc
	v_ldexp_f32 v20, v20, v21
	v_mul_f32_e32 v19, v20, v19
	v_cndmask_b32_e64 v19, 0, v19, s[68:69]
	v_cvt_pk_bf16_f32 v17, v18, v19
	ds_write_b64 v24, v[16:17] offset:96
	ds_read_b128 v[16:19], v118 offset:17408
	ds_read_b128 v[20:23], v118 offset:17472
	s_waitcnt lgkmcnt(1)
	v_mfma_f32_16x16x32_bf16 v[16:19], v[16:19], v[12:15], 0
	s_waitcnt lgkmcnt(0)
	v_mfma_f32_16x16x32_bf16 v[16:19], v[20:23], v[8:11], v[16:19]
	ds_read_b128 v[20:23], v118 offset:17536
	s_waitcnt lgkmcnt(0)
	v_mfma_f32_16x16x32_bf16 v[16:19], v[20:23], v[4:7], v[16:19]
	ds_read_b128 v[20:23], v118 offset:17600
	s_waitcnt lgkmcnt(0)
	v_mfma_f32_16x16x32_bf16 v[16:19], v[20:23], v[0:3], v[16:19]
	v_mul_f32_e32 v20, v113, v139
	v_cmp_gt_f32_e32 vcc, s34, v20
	s_nop 5
	v_mul_f32_e32 v16, 0x3db504f3, v16
	v_cndmask_b32_e32 v20, 0, v168, vcc
	v_fmac_f32_e32 v20, v113, v139
	v_exp_f32_e32 v20, v20
	v_cndmask_b32_e32 v21, 0, v171, vcc
	v_mul_f32_e32 v17, 0x3db504f3, v17
	v_mul_f32_e32 v18, 0x3db504f3, v18
	v_ldexp_f32 v20, v20, v21
	v_mul_f32_e32 v16, v20, v16
	v_mul_f32_e32 v20, v113, v140
	v_cmp_gt_f32_e32 vcc, s34, v20
	v_mul_f32_e32 v19, 0x3db504f3, v19
	v_cndmask_b32_e64 v16, 0, v16, s[70:71]
	v_cndmask_b32_e32 v20, 0, v168, vcc
	v_fmac_f32_e32 v20, v113, v140
	v_exp_f32_e32 v20, v20
	v_cndmask_b32_e32 v21, 0, v171, vcc
	v_ldexp_f32 v20, v20, v21
	v_mul_f32_e32 v17, v20, v17
	v_mul_f32_e32 v20, v113, v141
	v_cmp_gt_f32_e32 vcc, s34, v20
	v_cndmask_b32_e64 v17, 0, v17, s[72:73]
	v_cvt_pk_bf16_f32 v16, v16, v17
	s_nop 0
	v_cndmask_b32_e32 v20, 0, v168, vcc
	v_fmac_f32_e32 v20, v113, v141
	v_exp_f32_e32 v20, v20
	v_cndmask_b32_e32 v21, 0, v171, vcc
	v_ldexp_f32 v20, v20, v21
	v_mul_f32_e32 v18, v20, v18
	v_mul_f32_e32 v20, v113, v142
	v_cmp_gt_f32_e32 vcc, s34, v20
	v_cndmask_b32_e64 v18, 0, v18, s[74:75]
	s_nop 0
	v_cndmask_b32_e32 v20, 0, v168, vcc
	v_fmac_f32_e32 v20, v113, v142
	v_exp_f32_e32 v20, v20
	v_cndmask_b32_e32 v21, 0, v171, vcc
	v_ldexp_f32 v20, v20, v21
	v_mul_f32_e32 v19, v20, v19
	v_cndmask_b32_e64 v19, 0, v19, s[76:77]
	v_cvt_pk_bf16_f32 v17, v18, v19
	ds_write_b64 v24, v[16:17] offset:128
	ds_read_b128 v[16:19], v118 offset:21760
	ds_read_b128 v[20:23], v118 offset:21824
	s_waitcnt lgkmcnt(1)
	v_mfma_f32_16x16x32_bf16 v[16:19], v[16:19], v[12:15], 0
	s_waitcnt lgkmcnt(0)
	v_mfma_f32_16x16x32_bf16 v[16:19], v[20:23], v[8:11], v[16:19]
	ds_read_b128 v[20:23], v118 offset:21888
	s_waitcnt lgkmcnt(0)
	v_mfma_f32_16x16x32_bf16 v[16:19], v[20:23], v[4:7], v[16:19]
	ds_read_b128 v[20:23], v118 offset:21952
	s_waitcnt lgkmcnt(0)
	v_mfma_f32_16x16x32_bf16 v[16:19], v[20:23], v[0:3], v[16:19]
	v_mul_f32_e32 v20, v113, v143
	v_cmp_gt_f32_e32 vcc, s34, v20
	s_nop 5
	v_mul_f32_e32 v16, 0x3db504f3, v16
	v_cndmask_b32_e32 v20, 0, v168, vcc
	v_fmac_f32_e32 v20, v113, v143
	v_exp_f32_e32 v20, v20
	v_cndmask_b32_e32 v21, 0, v171, vcc
	v_mul_f32_e32 v17, 0x3db504f3, v17
	v_mul_f32_e32 v18, 0x3db504f3, v18
	v_ldexp_f32 v20, v20, v21
	v_mul_f32_e32 v16, v20, v16
	v_mul_f32_e32 v20, v113, v144
	v_cmp_gt_f32_e32 vcc, s34, v20
	v_mul_f32_e32 v19, 0x3db504f3, v19
	v_cndmask_b32_e64 v16, 0, v16, s[78:79]
	v_cndmask_b32_e32 v20, 0, v168, vcc
	v_fmac_f32_e32 v20, v113, v144
	v_exp_f32_e32 v20, v20
	v_cndmask_b32_e32 v21, 0, v171, vcc
	v_ldexp_f32 v20, v20, v21
	v_mul_f32_e32 v17, v20, v17
	v_mul_f32_e32 v20, v113, v145
	v_cmp_gt_f32_e32 vcc, s34, v20
	v_cndmask_b32_e64 v17, 0, v17, s[80:81]
	v_cvt_pk_bf16_f32 v16, v16, v17
	s_nop 0
	v_cndmask_b32_e32 v20, 0, v168, vcc
	v_fmac_f32_e32 v20, v113, v145
	v_exp_f32_e32 v20, v20
	v_cndmask_b32_e32 v21, 0, v171, vcc
	v_ldexp_f32 v20, v20, v21
	v_mul_f32_e32 v18, v20, v18
	v_mul_f32_e32 v20, v113, v146
	v_cmp_gt_f32_e32 vcc, s34, v20
	v_cndmask_b32_e64 v18, 0, v18, s[82:83]
	s_nop 0
	v_cndmask_b32_e32 v20, 0, v168, vcc
	v_fmac_f32_e32 v20, v113, v146
	v_exp_f32_e32 v20, v20
	v_cndmask_b32_e32 v21, 0, v171, vcc
	v_ldexp_f32 v20, v20, v21
	v_mul_f32_e32 v19, v20, v19
	v_cndmask_b32_e64 v19, 0, v19, s[84:85]
	v_cvt_pk_bf16_f32 v17, v18, v19
	ds_write_b64 v24, v[16:17] offset:160
	ds_read_b128 v[16:19], v118 offset:26112
	ds_read_b128 v[20:23], v118 offset:26176
	s_waitcnt lgkmcnt(1)
; #define LAS __attribute__((address_space(3)))
; __device__ __forceinline__ unsigned pk_bf16(float lo, float hi) { unsigned r; asm volatile("v_cvt_pk_bf16_f32 %0, %1, %2" : "=v"(r) : "v"(lo), "v"(hi)); return r; }
; __device__ __forceinline__ f32x4 mfma16(bf16x8 a, bf16x8 b, f32x4 c) { return __builtin_amdgcn_mfma_f32_16x16x32_bf16(a, b, c, 0, 0, 0); }
; __device__ __forceinline__ void lds_wave_sync() { asm volatile("s_waitcnt lgkmcnt(0)" ::: "memory"); }
; __device__ __forceinline__ void ret_out_unit(int b, int h, int c, LAS unsigned char* lds, const bf16_t* PROJ, const float* KV, bf16_t* H, int tid) {
;     ...
;     for (int cb = 0; cb < 8; ++cb) { f32x4 acc = {0.f, 0.f, 0.f, 0.f};
; #pragma unroll
;         for (int kk = 0; kk < 4; ++kk) { const bf16x8 kf = *(const LAS bf16x8*)(Ks + (16 * cb + fr) * 272 + (32 * kk + 8 * fq) * 2); acc = mfma16(kf, qf[kk], acc); }
;         float v[4];
; #pragma unroll
;         for (int t = 0; t < 4; ++t) { const int dl = i - (16 * cb + 4 * fq + t); v[t] = dl >= 0 ? acc[t] * 0.08838834764831845f * exp2f(lg2 * (float)dl) : 0.f; }
;         u32x2 w; w.x = pk_bf16(v[0], v[1]); w.y = pk_bf16(v[2], v[3]);
;         *(LAS u32x2*)(SC + i * 272 + (16 * cb + 4 * fq) * 2) = w; }
;     lds_wave_sync();
;     f32x4 o1[8], o2[8];
; #pragma unroll
;     for (int cb = 0; cb < 8; ++cb) { o1[cb] = (f32x4){0.f, 0.f, 0.f, 0.f}; o2[cb] = (f32x4){0.f, 0.f, 0.f, 0.f}; }
; #pragma unroll
;     for (int kk = 0; kk < 4; ++kk) { const bf16x8 sf = *(const LAS bf16x8*)(SC + i * 272 + (32 * kk + 8 * fq) * 2);
; #pragma unroll
;         for (int cb = 0; cb < 8; ++cb) { const bf16x8 vf = *(const LAS bf16x8*)(VT + (16 * cb + fr) * 272 + (32 * kk + 8 * fq) * 2); o1[cb] = mfma16(vf, sf, o1[cb]);
;             const bf16x8 tf = *(const LAS bf16x8*)(ST + (16 * cb + fr) * 272 + (32 * kk + 8 * fq) * 2); o2[cb] = mfma16(tf, qf[kk], o2[cb]); } }
	v_mfma_f32_16x16x32_bf16 v[16:19], v[16:19], v[12:15], 0
	s_waitcnt lgkmcnt(0)
	v_mfma_f32_16x16x32_bf16 v[16:19], v[20:23], v[8:11], v[16:19]
	ds_read_b128 v[20:23], v118 offset:26240
	s_waitcnt lgkmcnt(0)
	v_mfma_f32_16x16x32_bf16 v[16:19], v[20:23], v[4:7], v[16:19]
	ds_read_b128 v[20:23], v118 offset:26304
	s_waitcnt lgkmcnt(0)
	v_mfma_f32_16x16x32_bf16 v[16:19], v[20:23], v[0:3], v[16:19]
	v_mul_f32_e32 v20, v113, v147
	v_cmp_gt_f32_e32 vcc, s34, v20
	s_nop 5
	v_mul_f32_e32 v16, 0x3db504f3, v16
	v_cndmask_b32_e32 v20, 0, v168, vcc
	v_fmac_f32_e32 v20, v113, v147
	v_exp_f32_e32 v20, v20
	v_cndmask_b32_e32 v21, 0, v171, vcc
	v_mul_f32_e32 v17, 0x3db504f3, v17
	v_mul_f32_e32 v18, 0x3db504f3, v18
	v_ldexp_f32 v20, v20, v21
	v_mul_f32_e32 v16, v20, v16
	v_mul_f32_e32 v20, v113, v148
	v_cmp_gt_f32_e32 vcc, s34, v20
	v_mul_f32_e32 v19, 0x3db504f3, v19
	v_cndmask_b32_e64 v16, 0, v16, s[86:87]
	v_cndmask_b32_e32 v20, 0, v168, vcc
	v_fmac_f32_e32 v20, v113, v148
	v_exp_f32_e32 v20, v20
	v_cndmask_b32_e32 v21, 0, v171, vcc
	v_ldexp_f32 v20, v20, v21
	v_mul_f32_e32 v17, v20, v17
	v_mul_f32_e32 v20, v113, v149
	v_cmp_gt_f32_e32 vcc, s34, v20
	v_cndmask_b32_e64 v17, 0, v17, s[88:89]
	v_cvt_pk_bf16_f32 v16, v16, v17
	s_nop 0
	v_cndmask_b32_e32 v20, 0, v168, vcc
	v_fmac_f32_e32 v20, v113, v149
	v_exp_f32_e32 v20, v20
	v_cndmask_b32_e32 v21, 0, v171, vcc
	v_ldexp_f32 v20, v20, v21
	v_mul_f32_e32 v18, v20, v18
	v_mul_f32_e32 v20, v113, v150
	v_cmp_gt_f32_e32 vcc, s34, v20
	v_cndmask_b32_e64 v18, 0, v18, s[90:91]
	s_nop 0
	v_cndmask_b32_e32 v20, 0, v168, vcc
	v_fmac_f32_e32 v20, v113, v150
	v_exp_f32_e32 v20, v20
	v_cndmask_b32_e32 v21, 0, v171, vcc
	v_ldexp_f32 v20, v20, v21
	v_mul_f32_e32 v19, v20, v19
	v_cndmask_b32_e64 v19, 0, v19, s[92:93]
	v_cvt_pk_bf16_f32 v17, v18, v19
	ds_write_b64 v24, v[16:17] offset:192
	ds_read_b128 v[16:19], v118 offset:30464
	ds_read_b128 v[20:23], v118 offset:30528
	s_waitcnt lgkmcnt(1)
	v_mfma_f32_16x16x32_bf16 v[16:19], v[16:19], v[12:15], 0
	s_waitcnt lgkmcnt(0)
	v_mfma_f32_16x16x32_bf16 v[16:19], v[20:23], v[8:11], v[16:19]
	ds_read_b128 v[20:23], v118 offset:30592
	s_waitcnt lgkmcnt(0)
	v_mfma_f32_16x16x32_bf16 v[16:19], v[20:23], v[4:7], v[16:19]
	ds_read_b128 v[20:23], v118 offset:30656
	s_waitcnt lgkmcnt(0)
	v_mfma_f32_16x16x32_bf16 v[16:19], v[20:23], v[0:3], v[16:19]
	v_mul_f32_e32 v20, v113, v151
	v_cmp_gt_f32_e32 vcc, s34, v20
	s_nop 5
	v_mul_f32_e32 v16, 0x3db504f3, v16
	v_cndmask_b32_e32 v20, 0, v168, vcc
	v_fmac_f32_e32 v20, v113, v151
	v_exp_f32_e32 v20, v20
	v_cndmask_b32_e32 v21, 0, v171, vcc
	v_mul_f32_e32 v17, 0x3db504f3, v17
	v_mul_f32_e32 v18, 0x3db504f3, v18
	v_ldexp_f32 v20, v20, v21
	v_mul_f32_e32 v16, v20, v16
	v_mul_f32_e32 v20, v113, v152
	v_cmp_gt_f32_e32 vcc, s34, v20
	v_mul_f32_e32 v19, 0x3db504f3, v19
	v_cndmask_b32_e64 v16, 0, v16, s[94:95]
	v_cndmask_b32_e32 v20, 0, v168, vcc
	v_fmac_f32_e32 v20, v113, v152
	v_exp_f32_e32 v20, v20
	v_cndmask_b32_e32 v21, 0, v171, vcc
	v_ldexp_f32 v20, v20, v21
	v_mul_f32_e32 v17, v20, v17
	v_mul_f32_e32 v20, v113, v153
	v_cmp_gt_f32_e32 vcc, s34, v20
	v_cndmask_b32_e64 v17, 0, v17, s[96:97]
	v_cvt_pk_bf16_f32 v16, v16, v17
	s_nop 0
	v_cndmask_b32_e32 v20, 0, v168, vcc
	v_fmac_f32_e32 v20, v113, v153
	v_exp_f32_e32 v20, v20
	v_cndmask_b32_e32 v21, 0, v171, vcc
	v_ldexp_f32 v20, v20, v21
	v_mul_f32_e32 v18, v20, v18
	v_mul_f32_e32 v20, v113, v154
	v_cmp_gt_f32_e32 vcc, s34, v20
	v_cndmask_b32_e64 v18, 0, v18, s[0:1]
	s_nop 0
	v_cndmask_b32_e32 v20, 0, v168, vcc
	v_fmac_f32_e32 v20, v113, v154
	v_exp_f32_e32 v20, v20
	v_cndmask_b32_e32 v21, 0, v171, vcc
	v_ldexp_f32 v20, v20, v21
	v_mul_f32_e32 v19, v20, v19
	v_cndmask_b32_e64 v19, 0, v19, s[4:5]
	v_cvt_pk_bf16_f32 v17, v18, v19
	ds_write_b64 v24, v[16:17] offset:224
	s_waitcnt lgkmcnt(0)
	ds_read_b128 v[16:19], v128
	ds_read_b128 v[20:23], v118 offset:34816
	s_waitcnt lgkmcnt(0)
	v_mfma_f32_16x16x32_bf16 v[32:35], v[20:23], v[16:19], 0
	ds_read_b128 v[20:23], v202
	s_waitcnt lgkmcnt(0)
	v_mfma_f32_16x16x32_bf16 v[212:215], v[20:23], v[12:15], 0
	ds_read_b128 v[20:23], v118 offset:39168
	s_waitcnt lgkmcnt(0)
	v_mfma_f32_16x16x32_bf16 v[72:75], v[20:23], v[16:19], 0
	ds_read_b128 v[20:23], v202 offset:4352
	s_waitcnt lgkmcnt(0)
	v_mfma_f32_16x16x32_bf16 v[76:79], v[20:23], v[12:15], 0
	ds_read_b128 v[20:23], v118 offset:43520
	s_waitcnt lgkmcnt(0)
	v_mfma_f32_16x16x32_bf16 v[64:67], v[20:23], v[16:19], 0
	ds_read_b128 v[20:23], v202 offset:8704
	s_waitcnt lgkmcnt(0)
	v_mfma_f32_16x16x32_bf16 v[68:71], v[20:23], v[12:15], 0
	ds_read_b128 v[20:23], v118 offset:47872
	s_waitcnt lgkmcnt(0)
	v_mfma_f32_16x16x32_bf16 v[52:55], v[20:23], v[16:19], 0
	ds_read_b128 v[20:23], v202 offset:13056
	s_waitcnt lgkmcnt(0)
	v_mfma_f32_16x16x32_bf16 v[56:59], v[20:23], v[12:15], 0
	ds_read_b128 v[20:23], v118 offset:52224
	s_waitcnt lgkmcnt(0)
	v_mfma_f32_16x16x32_bf16 v[44:47], v[20:23], v[16:19], 0
	ds_read_b128 v[20:23], v202 offset:17408
	s_waitcnt lgkmcnt(0)
	v_mfma_f32_16x16x32_bf16 v[48:51], v[20:23], v[12:15], 0
	ds_read_b128 v[20:23], v118 offset:56576
	s_waitcnt lgkmcnt(0)
	v_mfma_f32_16x16x32_bf16 v[36:39], v[20:23], v[16:19], 0
	ds_read_b128 v[20:23], v202 offset:21760
	s_waitcnt lgkmcnt(0)
	v_mfma_f32_16x16x32_bf16 v[40:43], v[20:23], v[12:15], 0
	ds_read_b128 v[20:23], v118 offset:60928
	s_waitcnt lgkmcnt(0)
	v_mfma_f32_16x16x32_bf16 v[24:27], v[20:23], v[16:19], 0
	ds_read_b128 v[20:23], v202 offset:26112
	s_waitcnt lgkmcnt(0)
	v_mfma_f32_16x16x32_bf16 v[28:31], v[20:23], v[12:15], 0
	ds_read_b128 v[20:23], v118 offset:65280
	s_waitcnt lgkmcnt(0)
; #define LAS __attribute__((address_space(3)))
; __device__ __forceinline__ f32x4 mfma16(bf16x8 a, bf16x8 b, f32x4 c) { return __builtin_amdgcn_mfma_f32_16x16x32_bf16(a, b, c, 0, 0, 0); }
; __device__ __forceinline__ void ret_out_unit(int b, int h, int c, LAS unsigned char* lds, const bf16_t* PROJ, const float* KV, bf16_t* H, int tid) {
;     ...
; #pragma unroll
;     for (int kk = 0; kk < 4; ++kk) { const bf16x8 sf = *(const LAS bf16x8*)(SC + i * 272 + (32 * kk + 8 * fq) * 2);
; #pragma unroll
;         for (int cb = 0; cb < 8; ++cb) { const bf16x8 vf = *(const LAS bf16x8*)(VT + (16 * cb + fr) * 272 + (32 * kk + 8 * fq) * 2); o1[cb] = mfma16(vf, sf, o1[cb]);
;             const bf16x8 tf = *(const LAS bf16x8*)(ST + (16 * cb + fr) * 272 + (32 * kk + 8 * fq) * 2); o2[cb] = mfma16(tf, qf[kk], o2[cb]); } }
	v_mfma_f32_16x16x32_bf16 v[20:23], v[20:23], v[16:19], 0
	ds_read_b128 v[16:19], v202 offset:30464
	s_waitcnt lgkmcnt(0)
	v_mfma_f32_16x16x32_bf16 v[16:19], v[16:19], v[12:15], 0
	ds_read_b128 v[60:63], v128 offset:64
	ds_read_b128 v[12:15], v118 offset:34880
	s_waitcnt lgkmcnt(0)
	v_mfma_f32_16x16x32_bf16 v[32:35], v[12:15], v[60:63], v[32:35]
	v_add_u32_e32 v12, v156, v155
	ds_read_b128 v[12:15], v12
	s_waitcnt lgkmcnt(0)
	v_mfma_f32_16x16x32_bf16 v[12:15], v[12:15], v[8:11], v[212:215]
	s_nop 2
	ds_read_b128 v[212:215], v118 offset:39232
	s_waitcnt lgkmcnt(0)
	v_mfma_f32_16x16x32_bf16 v[72:75], v[212:215], v[60:63], v[72:75]
	ds_read_b128 v[212:215], v203 offset:4352
	s_waitcnt lgkmcnt(0)
	v_mfma_f32_16x16x32_bf16 v[76:79], v[212:215], v[8:11], v[76:79]
	ds_read_b128 v[212:215], v118 offset:43584
	s_waitcnt lgkmcnt(0)
	v_mfma_f32_16x16x32_bf16 v[64:67], v[212:215], v[60:63], v[64:67]
	ds_read_b128 v[212:215], v203 offset:8704
	s_waitcnt lgkmcnt(0)
	v_mfma_f32_16x16x32_bf16 v[68:71], v[212:215], v[8:11], v[68:71]
	ds_read_b128 v[212:215], v118 offset:47936
	s_waitcnt lgkmcnt(0)
	v_mfma_f32_16x16x32_bf16 v[52:55], v[212:215], v[60:63], v[52:55]
	ds_read_b128 v[212:215], v203 offset:13056
	s_waitcnt lgkmcnt(0)
	v_mfma_f32_16x16x32_bf16 v[56:59], v[212:215], v[8:11], v[56:59]
	ds_read_b128 v[212:215], v118 offset:52288
	s_waitcnt lgkmcnt(0)
	v_mfma_f32_16x16x32_bf16 v[44:47], v[212:215], v[60:63], v[44:47]
	ds_read_b128 v[212:215], v203 offset:17408
	s_waitcnt lgkmcnt(0)
	v_mfma_f32_16x16x32_bf16 v[48:51], v[212:215], v[8:11], v[48:51]
	ds_read_b128 v[212:215], v118 offset:56640
	s_waitcnt lgkmcnt(0)
	v_mfma_f32_16x16x32_bf16 v[36:39], v[212:215], v[60:63], v[36:39]
	ds_read_b128 v[212:215], v203 offset:21760
	s_waitcnt lgkmcnt(0)
	v_mfma_f32_16x16x32_bf16 v[40:43], v[212:215], v[8:11], v[40:43]
	ds_read_b128 v[212:215], v118 offset:60992
	s_waitcnt lgkmcnt(0)
	v_mfma_f32_16x16x32_bf16 v[24:27], v[212:215], v[60:63], v[24:27]
	ds_read_b128 v[212:215], v203 offset:26112
	s_waitcnt lgkmcnt(0)
	v_mfma_f32_16x16x32_bf16 v[28:31], v[212:215], v[8:11], v[28:31]
	ds_read_b128 v[212:215], v118 offset:65344
	s_waitcnt lgkmcnt(0)
	v_mfma_f32_16x16x32_bf16 v[20:23], v[212:215], v[60:63], v[20:23]
	ds_read_b128 v[60:63], v203 offset:30464
	s_waitcnt lgkmcnt(0)
	v_mfma_f32_16x16x32_bf16 v[60:63], v[60:63], v[8:11], v[16:19]
	ds_read_b128 v[8:11], v128 offset:128
	s_nop 1
	ds_read_b128 v[16:19], v118 offset:34944
	s_waitcnt lgkmcnt(0)
	v_mfma_f32_16x16x32_bf16 v[32:35], v[16:19], v[8:11], v[32:35]
	v_add_u32_e32 v16, v156, v157
	ds_read_b128 v[16:19], v16
	s_waitcnt lgkmcnt(0)
	v_mfma_f32_16x16x32_bf16 v[212:215], v[16:19], v[4:7], v[12:15]
	s_nop 2
	ds_read_b128 v[12:15], v118 offset:39296
	ds_read_b128 v[16:19], v204 offset:26112
	s_waitcnt lgkmcnt(1)
	v_mfma_f32_16x16x32_bf16 v[72:75], v[12:15], v[8:11], v[72:75]
	ds_read_b128 v[12:15], v204 offset:4352
	s_waitcnt lgkmcnt(0)
	v_mfma_f32_16x16x32_bf16 v[76:79], v[12:15], v[4:7], v[76:79]
	ds_read_b128 v[12:15], v118 offset:43648
	s_waitcnt lgkmcnt(0)
	v_mfma_f32_16x16x32_bf16 v[64:67], v[12:15], v[8:11], v[64:67]
	ds_read_b128 v[12:15], v204 offset:8704
	s_waitcnt lgkmcnt(0)
	v_mfma_f32_16x16x32_bf16 v[68:71], v[12:15], v[4:7], v[68:71]
	ds_read_b128 v[12:15], v118 offset:48000
	s_waitcnt lgkmcnt(0)
	v_mfma_f32_16x16x32_bf16 v[52:55], v[12:15], v[8:11], v[52:55]
	ds_read_b128 v[12:15], v204 offset:13056
	s_waitcnt lgkmcnt(0)
	v_mfma_f32_16x16x32_bf16 v[56:59], v[12:15], v[4:7], v[56:59]
	ds_read_b128 v[12:15], v118 offset:52352
	s_waitcnt lgkmcnt(0)
	v_mfma_f32_16x16x32_bf16 v[44:47], v[12:15], v[8:11], v[44:47]
	ds_read_b128 v[12:15], v204 offset:17408
	s_waitcnt lgkmcnt(0)
	v_mfma_f32_16x16x32_bf16 v[48:51], v[12:15], v[4:7], v[48:51]
	ds_read_b128 v[12:15], v118 offset:56704
	s_waitcnt lgkmcnt(0)
	v_mfma_f32_16x16x32_bf16 v[36:39], v[12:15], v[8:11], v[36:39]
	ds_read_b128 v[12:15], v204 offset:21760
	s_waitcnt lgkmcnt(0)
	v_mfma_f32_16x16x32_bf16 v[40:43], v[12:15], v[4:7], v[40:43]
	ds_read_b128 v[12:15], v118 offset:61056
	s_waitcnt lgkmcnt(0)
	v_mfma_f32_16x16x32_bf16 v[12:15], v[12:15], v[8:11], v[24:27]
	s_nop 2
	ds_read_b128 v[24:27], v118 offset:65408
	s_waitcnt lgkmcnt(0)
	v_mfma_f32_16x16x32_bf16 v[8:11], v[24:27], v[8:11], v[20:23]
	s_nop 2
	ds_read_b128 v[20:23], v204 offset:30464
	v_mfma_f32_16x16x32_bf16 v[16:19], v[16:19], v[4:7], v[28:31]
	s_waitcnt lgkmcnt(0)
	v_mfma_f32_16x16x32_bf16 v[4:7], v[20:23], v[4:7], v[60:63]
	ds_read_b128 v[20:23], v128 offset:192
	ds_read_b128 v[24:27], v118 offset:35008
	v_add_u32_e32 v28, v156, v158
	ds_read_b128 v[28:31], v28
	s_waitcnt lgkmcnt(1)
	v_mfma_f32_16x16x32_bf16 v[24:27], v[24:27], v[20:23], v[32:35]
	s_nop 2
	ds_read_b128 v[32:35], v118 offset:39360
	s_waitcnt lgkmcnt(0)
	v_mfma_f32_16x16x32_bf16 v[60:63], v[32:35], v[20:23], v[72:75]
	ds_read_b128 v[32:35], v205 offset:4352
	s_waitcnt lgkmcnt(0)
	v_mfma_f32_16x16x32_bf16 v[72:75], v[32:35], v[0:3], v[76:79]
	ds_read_b128 v[32:35], v118 offset:43712
	s_waitcnt lgkmcnt(0)
	v_mfma_f32_16x16x32_bf16 v[64:67], v[32:35], v[20:23], v[64:67]
	ds_read_b128 v[32:35], v205 offset:8704
	s_waitcnt lgkmcnt(0)
	v_mfma_f32_16x16x32_bf16 v[68:71], v[32:35], v[0:3], v[68:71]
	ds_read_b128 v[32:35], v118 offset:48064
	s_waitcnt lgkmcnt(0)
	v_mfma_f32_16x16x32_bf16 v[52:55], v[32:35], v[20:23], v[52:55]
	ds_read_b128 v[32:35], v205 offset:13056
	s_waitcnt lgkmcnt(0)
	v_mfma_f32_16x16x32_bf16 v[56:59], v[32:35], v[0:3], v[56:59]
	ds_read_b128 v[32:35], v118 offset:52416
	s_waitcnt lgkmcnt(0)
	v_mfma_f32_16x16x32_bf16 v[44:47], v[32:35], v[20:23], v[44:47]
	ds_read_b128 v[32:35], v205 offset:17408
	s_waitcnt lgkmcnt(0)
; #define LAS __attribute__((address_space(3)))
; __device__ __forceinline__ f32x4 mfma16(bf16x8 a, bf16x8 b, f32x4 c) { return __builtin_amdgcn_mfma_f32_16x16x32_bf16(a, b, c, 0, 0, 0); }
; __device__ __forceinline__ void ret_out_unit(int b, int h, int c, LAS unsigned char* lds, const bf16_t* PROJ, const float* KV, bf16_t* H, int tid) {
;     ...
;     for (int kk = 0; kk < 4; ++kk) { const bf16x8 sf = *(const LAS bf16x8*)(SC + i * 272 + (32 * kk + 8 * fq) * 2);
; #pragma unroll
;         for (int cb = 0; cb < 8; ++cb) { const bf16x8 vf = *(const LAS bf16x8*)(VT + (16 * cb + fr) * 272 + (32 * kk + 8 * fq) * 2); o1[cb] = mfma16(vf, sf, o1[cb]);
;             const bf16x8 tf = *(const LAS bf16x8*)(ST + (16 * cb + fr) * 272 + (32 * kk + 8 * fq) * 2); o2[cb] = mfma16(tf, qf[kk], o2[cb]); } }
;     const float rd = exp2f(lg2 * (float)(i + 1));
;     float ss = 0.f;
; #pragma unroll
;     for (int cb = 0; cb < 8; ++cb) { o1[cb] = o1[cb] + o2[cb] * rd; ss += o1[cb][0] * o1[cb][0] + o1[cb][1] * o1[cb][1] + o1[cb][2] * o1[cb][2] + o1[cb][3] * o1[cb][3]; }
;     ss += __shfl_xor(ss, 16); ss += __shfl_xor(ss, 32);
;     const float rinv = rsqrtf(ss * (1.0f / 128.0f) + EPS);
; #pragma unroll
;     for (int cb = 0; cb < 8; ++cb) { const u32x2 gw = *(const u32x2*)(PROJ + qrow * EIN + 3072 + h * 128 + 16 * cb + 4 * fq);
	v_mfma_f32_16x16x32_bf16 v[48:51], v[32:35], v[0:3], v[48:51]
	ds_read_b128 v[32:35], v118 offset:56768
	s_waitcnt lgkmcnt(0)
	v_mfma_f32_16x16x32_bf16 v[36:39], v[32:35], v[20:23], v[36:39]
	ds_read_b128 v[32:35], v205 offset:21760
	s_waitcnt lgkmcnt(0)
	v_mfma_f32_16x16x32_bf16 v[40:43], v[32:35], v[0:3], v[40:43]
	ds_read_b128 v[32:35], v118 offset:61120
	s_waitcnt lgkmcnt(0)
	v_mfma_f32_16x16x32_bf16 v[76:79], v[32:35], v[20:23], v[12:15]
	s_nop 2
	ds_read_b128 v[12:15], v205 offset:26112
	v_mfma_f32_16x16x32_bf16 v[28:31], v[28:31], v[0:3], v[212:215]
	s_waitcnt lgkmcnt(0)
	v_mfma_f32_16x16x32_bf16 v[212:215], v[12:15], v[0:3], v[16:19]
	ds_read_b128 v[12:15], v118 offset:65472
	s_waitcnt lgkmcnt(0)
	v_mfma_f32_16x16x32_bf16 v[216:219], v[12:15], v[20:23], v[8:11]
	s_nop 2
	ds_read_b128 v[8:11], v205 offset:30464
	s_waitcnt lgkmcnt(0)
	v_mfma_f32_16x16x32_bf16 v[2:5], v[8:11], v[0:3], v[4:7]
	v_mul_f32_e32 v0, v113, v159
	v_cmp_gt_f32_e32 vcc, s34, v0
	s_nop 1
	v_cndmask_b32_e32 v0, 0, v168, vcc
	v_fmac_f32_e32 v0, v113, v159
	v_exp_f32_e32 v0, v0
	v_cndmask_b32_e32 v1, 0, v171, vcc
	v_mov_b32_e32 v113, v129
	v_ldexp_f32 v6, v0, v1
	v_pk_fma_f32 v[32:33], v[6:7], v[30:31], v[26:27] op_sel_hi:[0,1,1]
	v_pk_fma_f32 v[34:35], v[6:7], v[28:29], v[24:25] op_sel_hi:[0,1,1]
	v_pk_fma_f32 v[30:31], v[6:7], v[72:73], v[60:61] op_sel_hi:[0,1,1]
	v_mov_b32_e32 v8, v35
	v_mov_b32_e32 v9, v31
	v_pk_fma_f32 v[28:29], v[6:7], v[74:75], v[62:63] op_sel_hi:[0,1,1]
	v_mov_b32_e32 v0, v34
	v_mov_b32_e32 v1, v30
	v_pk_mul_f32 v[8:9], v[8:9], v[8:9]
	v_pk_fma_f32 v[26:27], v[6:7], v[68:69], v[64:65] op_sel_hi:[0,1,1]
	v_pk_fma_f32 v[0:1], v[0:1], v[0:1], v[8:9]
	v_mov_b32_e32 v8, v32
	v_mov_b32_e32 v9, v28
	v_pk_fma_f32 v[0:1], v[8:9], v[8:9], v[0:1]
	v_mov_b32_e32 v8, v33
	v_mov_b32_e32 v9, v29
	v_pk_fma_f32 v[22:23], v[6:7], v[56:57], v[52:53] op_sel_hi:[0,1,1]
	v_pk_fma_f32 v[60:61], v[8:9], v[8:9], v[0:1]
	v_mov_b32_e32 v8, v27
	v_mov_b32_e32 v9, v23
	v_pk_fma_f32 v[24:25], v[6:7], v[70:71], v[66:67] op_sel_hi:[0,1,1]
	v_pk_fma_f32 v[20:21], v[6:7], v[58:59], v[54:55] op_sel_hi:[0,1,1]
	v_mov_b32_e32 v0, v26
	v_mov_b32_e32 v1, v22
	v_pk_mul_f32 v[8:9], v[8:9], v[8:9]
	v_pk_fma_f32 v[18:19], v[6:7], v[48:49], v[44:45] op_sel_hi:[0,1,1]
	v_pk_fma_f32 v[0:1], v[0:1], v[0:1], v[8:9]
	v_mov_b32_e32 v8, v24
	v_mov_b32_e32 v9, v20
	v_pk_fma_f32 v[0:1], v[8:9], v[8:9], v[0:1]
	v_mov_b32_e32 v8, v25
	v_mov_b32_e32 v9, v21
	v_pk_fma_f32 v[14:15], v[6:7], v[40:41], v[36:37] op_sel_hi:[0,1,1]
	v_pk_fma_f32 v[52:53], v[8:9], v[8:9], v[0:1]
	v_mov_b32_e32 v8, v19
	v_mov_b32_e32 v9, v15
	v_pk_fma_f32 v[16:17], v[6:7], v[50:51], v[46:47] op_sel_hi:[0,1,1]
	v_pk_fma_f32 v[12:13], v[6:7], v[42:43], v[38:39] op_sel_hi:[0,1,1]
	v_mov_b32_e32 v0, v18
	v_mov_b32_e32 v1, v14
	v_pk_mul_f32 v[8:9], v[8:9], v[8:9]
	v_pk_fma_f32 v[10:11], v[6:7], v[212:213], v[76:77] op_sel_hi:[0,1,1]
	v_pk_fma_f32 v[0:1], v[0:1], v[0:1], v[8:9]
	v_mov_b32_e32 v8, v16
	v_mov_b32_e32 v9, v12
	v_pk_fma_f32 v[0:1], v[8:9], v[8:9], v[0:1]
	v_mov_b32_e32 v8, v17
	v_mov_b32_e32 v9, v13
	v_pk_fma_f32 v[2:3], v[6:7], v[2:3], v[216:217] op_sel_hi:[0,1,1]
	v_pk_fma_f32 v[36:37], v[8:9], v[8:9], v[0:1]
	v_pk_fma_f32 v[8:9], v[6:7], v[214:215], v[78:79] op_sel_hi:[0,1,1]
	v_pk_fma_f32 v[0:1], v[6:7], v[4:5], v[218:219] op_sel_hi:[0,1,1]
	v_mov_b32_e32 v6, v11
	v_mov_b32_e32 v7, v3
	v_mov_b32_e32 v4, v10
	v_mov_b32_e32 v5, v2
	v_pk_mul_f32 v[6:7], v[6:7], v[6:7]
	s_nop 0
	v_pk_fma_f32 v[4:5], v[4:5], v[4:5], v[6:7]
	v_mov_b32_e32 v6, v8
	v_mov_b32_e32 v7, v0
	v_pk_fma_f32 v[4:5], v[6:7], v[6:7], v[4:5]
	v_mov_b32_e32 v6, v9
	v_mov_b32_e32 v7, v1
	v_pk_fma_f32 v[4:5], v[6:7], v[6:7], v[4:5]
	v_add_f32_e32 v6, v60, v61
	v_add_f32_e32 v6, v6, v52
	v_add_f32_e32 v6, v6, v53
	v_add_f32_e32 v6, v6, v36
	v_add_f32_e32 v6, v6, v37
	v_add_f32_e32 v4, v6, v4
	v_and_b32_e32 v6, 64, v166
	v_add_f32_e32 v4, v4, v5
	v_xor_b32_e32 v5, 16, v166
	v_add_u32_e32 v6, 64, v6
	v_cmp_lt_i32_e32 vcc, v5, v6
	v_lshl_add_u64 v[36:37], v[116:117], 0, v[112:113]
	s_nop 0
	v_cndmask_b32_e32 v5, v166, v5, vcc
	v_lshlrev_b32_e32 v5, 2, v5
	ds_bpermute_b32 v5, v5, v4
	s_waitcnt lgkmcnt(0)
	v_add_f32_e32 v4, v4, v5
	v_xor_b32_e32 v5, 32, v166
	v_cmp_lt_i32_e32 vcc, v5, v6
	v_lshlrev_b64 v[6:7], 12, v[114:115]
	v_lshl_add_u64 v[6:7], s[18:19], 0, v[6:7]
	v_cndmask_b32_e32 v5, v166, v5, vcc
	v_lshlrev_b32_e32 v5, 2, v5
	ds_bpermute_b32 v5, v5, v4
	v_lshl_add_u64 v[6:7], v[6:7], 0, v[112:113]
	s_waitcnt lgkmcnt(0)
	v_add_f32_e32 v4, v4, v5
	v_fmamk_f32 v4, v4, 0x3c000000, v163
	v_cmp_gt_f32_e32 vcc, s23, v4
	v_mul_f32_e32 v5, 0x4b800000, v4
	s_nop 0
	v_cndmask_b32_e32 v4, v4, v5, vcc
	v_rsq_f32_e32 v4, v4
	s_nop 0
	v_mul_f32_e32 v5, 0x45800000, v4
	v_cndmask_b32_e32 v38, v4, v5, vcc
	v_lshl_add_u64 v[4:5], v[36:37], 0, s[14:15]
	v_add_co_u32_e32 v36, vcc, s33, v36
	v_mul_f32_e32 v34, v34, v38
	s_nop 0
	v_addc_co_u32_e32 v37, vcc, 0, v37, vcc
	global_load_dwordx2 v[40:41], v[36:37], off offset:2048
	v_mul_f32_e32 v35, v35, v38
	v_mul_f32_e32 v32, v32, v38
	v_mul_f32_e32 v33, v33, v38
	v_mul_f32_e32 v30, v30, v38
	v_mul_f32_e32 v31, v31, v38
	v_mul_f32_e32 v28, v28, v38
	v_mul_f32_e32 v29, v29, v38
	v_mul_f32_e32 v26, v26, v38
	v_mul_f32_e32 v27, v27, v38
	v_mul_f32_e32 v24, v24, v38
	v_mul_f32_e32 v25, v25, v38
	v_mul_f32_e32 v22, v22, v38
	v_mul_f32_e32 v23, v23, v38
	v_mul_f32_e32 v20, v20, v38
	v_mul_f32_e32 v21, v21, v38
	v_mul_f32_e32 v18, v18, v38
	v_mul_f32_e32 v19, v19, v38
	v_mul_f32_e32 v16, v16, v38
	v_mul_f32_e32 v17, v17, v38
	v_mul_f32_e32 v14, v14, v38
	v_mul_f32_e32 v15, v15, v38
	v_mul_f32_e32 v12, v12, v38
	v_mul_f32_e32 v13, v13, v38
	v_mul_f32_e32 v10, v10, v38
	v_mul_f32_e32 v11, v11, v38
	v_mul_f32_e32 v8, v8, v38
	v_mul_f32_e32 v9, v9, v38
	v_mul_f32_e32 v2, v2, v38
	v_mul_f32_e32 v3, v3, v38
	v_mul_f32_e32 v0, v0, v38
	v_mul_f32_e32 v1, v1, v38
	s_waitcnt vmcnt(0)
; __device__ __forceinline__ unsigned pk_bf16(float lo, float hi) { unsigned r; asm volatile("v_cvt_pk_bf16_f32 %0, %1, %2" : "=v"(r) : "v"(lo), "v"(hi)); return r; }
; __device__ __forceinline__ float bflo(unsigned w) { return __uint_as_float(w << 16); }
; __device__ __forceinline__ float bfhi(unsigned w) { return __uint_as_float(w & 0xffff0000u); }
; __device__ __forceinline__ float silu_f(float x) { return x / (1.0f + __expf(-x)); }
; __device__ __forceinline__ void ret_out_unit(int b, int h, int c, LAS unsigned char* lds, const bf16_t* PROJ, const float* KV, bf16_t* H, int tid) {
;     ...
;     for (int cb = 0; cb < 8; ++cb) { const u32x2 gw = *(const u32x2*)(PROJ + qrow * EIN + 3072 + h * 128 + 16 * cb + 4 * fq);
;         const float g0 = silu_f(bflo(gw.x)), g1 = silu_f(bfhi(gw.x)), g2 = silu_f(bflo(gw.y)), g3 = silu_f(bfhi(gw.y));
;         u32x2 w; w.x = pk_bf16(o1[cb][0] * rinv * g0, o1[cb][1] * rinv * g1); w.y = pk_bf16(o1[cb][2] * rinv * g2, o1[cb][3] * rinv * g3);
;         *(u32x2*)(H + qrow * DM + h * 128 + 16 * cb + 4 * fq) = w; }
	v_lshlrev_b32_e32 v36, 16, v40
	v_mul_f32_e32 v37, 0xbfb8aa3b, v36
	v_exp_f32_e32 v37, v37
	s_nop 0
	v_add_f32_e32 v37, 1.0, v37
	v_rcp_f32_e32 v42, v37
	s_nop 0
	v_mul_f32_e32 v36, v36, v42
	v_and_b32_e32 v37, 0xffff0000, v40
	v_mul_f32_e32 v39, 0xbfb8aa3b, v37
	v_exp_f32_e32 v39, v39
	v_mul_f32_e32 v34, v36, v34
	v_add_f32_e32 v39, 1.0, v39
	v_rcp_f32_e32 v42, v39
	s_nop 0
	v_mul_f32_e32 v37, v37, v42
	v_lshlrev_b32_e32 v39, 16, v41
	v_mul_f32_e32 v40, 0xbfb8aa3b, v39
	v_exp_f32_e32 v40, v40
	v_mul_f32_e32 v35, v37, v35
	v_cvt_pk_bf16_f32 v34, v34, v35
	v_add_f32_e32 v40, 1.0, v40
	v_rcp_f32_e32 v43, v40
	s_nop 0
	v_mul_f32_e32 v39, v39, v43
	v_and_b32_e32 v40, 0xffff0000, v41
	v_mul_f32_e32 v41, 0xbfb8aa3b, v40
	v_exp_f32_e32 v41, v41
	v_mul_f32_e32 v32, v39, v32
	v_add_f32_e32 v41, 1.0, v41
	v_rcp_f32_e32 v43, v41
	s_nop 0
	v_mul_f32_e32 v40, v40, v43
	v_mul_f32_e32 v33, v40, v33
	v_cvt_pk_bf16_f32 v35, v32, v33
	global_load_dwordx2 v[32:33], v[4:5], off offset:32
	s_nop 0
	global_store_dwordx2 v[6:7], v[34:35], off
	s_waitcnt vmcnt(1)
	v_lshlrev_b32_e32 v34, 16, v32
	v_mul_f32_e32 v35, 0xbfb8aa3b, v34
	v_exp_f32_e32 v35, v35
	v_and_b32_e32 v32, 0xffff0000, v32
	v_add_f32_e32 v35, 1.0, v35
	v_rcp_f32_e32 v37, v35
	s_nop 0
	v_mul_f32_e32 v34, v34, v37
	v_mul_f32_e32 v35, 0xbfb8aa3b, v32
	v_exp_f32_e32 v35, v35
	v_mul_f32_e32 v30, v34, v30
	v_add_f32_e32 v35, 1.0, v35
	v_rcp_f32_e32 v37, v35
	s_nop 0
	v_mul_f32_e32 v32, v32, v37
	v_lshlrev_b32_e32 v35, 16, v33
	v_mul_f32_e32 v36, 0xbfb8aa3b, v35
	v_exp_f32_e32 v36, v36
	v_and_b32_e32 v33, 0xffff0000, v33
	v_mul_f32_e32 v31, v32, v31
	v_cvt_pk_bf16_f32 v30, v30, v31
	v_add_f32_e32 v36, 1.0, v36
	v_rcp_f32_e32 v39, v36
	s_nop 0
	v_mul_f32_e32 v35, v35, v39
	v_mul_f32_e32 v36, 0xbfb8aa3b, v33
	v_exp_f32_e32 v36, v36
	v_mul_f32_e32 v28, v35, v28
	v_add_f32_e32 v36, 1.0, v36
	v_rcp_f32_e32 v39, v36
	s_nop 0
	v_mul_f32_e32 v33, v33, v39
	v_mul_f32_e32 v29, v33, v29
	v_cvt_pk_bf16_f32 v31, v28, v29
	global_load_dwordx2 v[28:29], v[4:5], off offset:64
	s_nop 0
	global_store_dwordx2 v[6:7], v[30:31], off offset:32
	s_waitcnt vmcnt(1)
	v_lshlrev_b32_e32 v30, 16, v28
	v_mul_f32_e32 v31, 0xbfb8aa3b, v30
	v_exp_f32_e32 v31, v31
	v_and_b32_e32 v28, 0xffff0000, v28
	v_add_f32_e32 v31, 1.0, v31
	v_rcp_f32_e32 v33, v31
	s_nop 0
	v_mul_f32_e32 v30, v30, v33
	v_mul_f32_e32 v31, 0xbfb8aa3b, v28
	v_exp_f32_e32 v31, v31
	v_mul_f32_e32 v26, v26, v30
	v_add_f32_e32 v31, 1.0, v31
	v_rcp_f32_e32 v33, v31
	s_nop 0
	v_mul_f32_e32 v28, v28, v33
	v_lshlrev_b32_e32 v31, 16, v29
	v_mul_f32_e32 v32, 0xbfb8aa3b, v31
	v_exp_f32_e32 v32, v32
	v_and_b32_e32 v29, 0xffff0000, v29
	v_mul_f32_e32 v27, v27, v28
	v_cvt_pk_bf16_f32 v26, v26, v27
	v_add_f32_e32 v32, 1.0, v32
	v_rcp_f32_e32 v34, v32
	s_nop 0
	v_mul_f32_e32 v31, v31, v34
	v_mul_f32_e32 v32, 0xbfb8aa3b, v29
	v_exp_f32_e32 v32, v32
	v_mul_f32_e32 v24, v24, v31
	v_add_f32_e32 v32, 1.0, v32
	v_rcp_f32_e32 v34, v32
	s_nop 0
	v_mul_f32_e32 v29, v29, v34
	v_mul_f32_e32 v25, v25, v29
	v_cvt_pk_bf16_f32 v27, v24, v25
	global_load_dwordx2 v[24:25], v[4:5], off offset:96
	s_nop 0
	global_store_dwordx2 v[6:7], v[26:27], off offset:64
	s_waitcnt vmcnt(1)
	v_lshlrev_b32_e32 v26, 16, v24
	v_mul_f32_e32 v27, 0xbfb8aa3b, v26
	v_exp_f32_e32 v27, v27
	v_and_b32_e32 v24, 0xffff0000, v24
	v_add_f32_e32 v27, 1.0, v27
	v_rcp_f32_e32 v29, v27
	s_nop 0
	v_mul_f32_e32 v26, v26, v29
	v_mul_f32_e32 v27, 0xbfb8aa3b, v24
	v_exp_f32_e32 v27, v27
	v_mul_f32_e32 v22, v22, v26
	v_add_f32_e32 v27, 1.0, v27
	v_rcp_f32_e32 v29, v27
	s_nop 0
	v_mul_f32_e32 v24, v24, v29
	v_lshlrev_b32_e32 v27, 16, v25
	v_mul_f32_e32 v28, 0xbfb8aa3b, v27
	v_exp_f32_e32 v28, v28
	v_and_b32_e32 v25, 0xffff0000, v25
	v_mul_f32_e32 v23, v23, v24
	v_cvt_pk_bf16_f32 v22, v22, v23
	v_add_f32_e32 v28, 1.0, v28
	v_rcp_f32_e32 v30, v28
	s_nop 0
	v_mul_f32_e32 v27, v27, v30
	v_mul_f32_e32 v28, 0xbfb8aa3b, v25
	v_exp_f32_e32 v28, v28
	v_mul_f32_e32 v20, v20, v27
	v_add_f32_e32 v28, 1.0, v28
	v_rcp_f32_e32 v30, v28
	s_nop 0
	v_mul_f32_e32 v25, v25, v30
	v_mul_f32_e32 v21, v21, v25
	v_cvt_pk_bf16_f32 v23, v20, v21
	global_load_dwordx2 v[20:21], v[4:5], off offset:128
	s_nop 0
	global_store_dwordx2 v[6:7], v[22:23], off offset:96
	s_waitcnt vmcnt(1)
; __device__ __forceinline__ unsigned pk_bf16(float lo, float hi) { unsigned r; asm volatile("v_cvt_pk_bf16_f32 %0, %1, %2" : "=v"(r) : "v"(lo), "v"(hi)); return r; }
; __device__ __forceinline__ float bflo(unsigned w) { return __uint_as_float(w << 16); }
; __device__ __forceinline__ float bfhi(unsigned w) { return __uint_as_float(w & 0xffff0000u); }
; __device__ __forceinline__ float silu_f(float x) { return x / (1.0f + __expf(-x)); }
; __device__ __forceinline__ void ret_out_unit(int b, int h, int c, LAS unsigned char* lds, const bf16_t* PROJ, const float* KV, bf16_t* H, int tid) {
;     ...
;     for (int cb = 0; cb < 8; ++cb) { const u32x2 gw = *(const u32x2*)(PROJ + qrow * EIN + 3072 + h * 128 + 16 * cb + 4 * fq);
;         const float g0 = silu_f(bflo(gw.x)), g1 = silu_f(bfhi(gw.x)), g2 = silu_f(bflo(gw.y)), g3 = silu_f(bfhi(gw.y));
;         u32x2 w; w.x = pk_bf16(o1[cb][0] * rinv * g0, o1[cb][1] * rinv * g1); w.y = pk_bf16(o1[cb][2] * rinv * g2, o1[cb][3] * rinv * g3);
;         *(u32x2*)(H + qrow * DM + h * 128 + 16 * cb + 4 * fq) = w; }
;     __syncthreads();
; __device__ __forceinline__ void phase_ret_out(const Ctx& P, LAS unsigned char* lds) {
;     ...
;     for (int u = P.bid; u < 512; u += P.nb) { const int c = u & 31, h = (u >> 5) & 7, b = u >> 8; ret_out_unit(b, h, c, lds, PROJ, KV, H, P.tid); }
	v_lshlrev_b32_e32 v22, 16, v20
	v_mul_f32_e32 v23, 0xbfb8aa3b, v22
	v_exp_f32_e32 v23, v23
	v_and_b32_e32 v20, 0xffff0000, v20
	v_add_f32_e32 v23, 1.0, v23
	v_rcp_f32_e32 v25, v23
	s_nop 0
	v_mul_f32_e32 v22, v22, v25
	v_mul_f32_e32 v23, 0xbfb8aa3b, v20
	v_exp_f32_e32 v23, v23
	v_mul_f32_e32 v18, v18, v22
	v_add_f32_e32 v23, 1.0, v23
	v_rcp_f32_e32 v25, v23
	s_nop 0
	v_mul_f32_e32 v20, v20, v25
	v_lshlrev_b32_e32 v23, 16, v21
	v_mul_f32_e32 v24, 0xbfb8aa3b, v23
	v_exp_f32_e32 v24, v24
	v_and_b32_e32 v21, 0xffff0000, v21
	v_mul_f32_e32 v19, v19, v20
	v_cvt_pk_bf16_f32 v18, v18, v19
	v_add_f32_e32 v24, 1.0, v24
	v_rcp_f32_e32 v26, v24
	s_nop 0
	v_mul_f32_e32 v23, v23, v26
	v_mul_f32_e32 v24, 0xbfb8aa3b, v21
	v_exp_f32_e32 v24, v24
	v_mul_f32_e32 v16, v16, v23
	v_add_f32_e32 v24, 1.0, v24
	v_rcp_f32_e32 v26, v24
	s_nop 0
	v_mul_f32_e32 v21, v21, v26
	v_mul_f32_e32 v17, v17, v21
	v_cvt_pk_bf16_f32 v19, v16, v17
	global_load_dwordx2 v[16:17], v[4:5], off offset:160
	s_nop 0
	global_store_dwordx2 v[6:7], v[18:19], off offset:128
	s_waitcnt vmcnt(1)
	v_lshlrev_b32_e32 v18, 16, v16
	v_mul_f32_e32 v19, 0xbfb8aa3b, v18
	v_exp_f32_e32 v19, v19
	v_and_b32_e32 v16, 0xffff0000, v16
	v_add_f32_e32 v19, 1.0, v19
	v_rcp_f32_e32 v21, v19
	s_nop 0
	v_mul_f32_e32 v18, v18, v21
	v_mul_f32_e32 v19, 0xbfb8aa3b, v16
	v_exp_f32_e32 v19, v19
	v_mul_f32_e32 v14, v14, v18
	v_add_f32_e32 v19, 1.0, v19
	v_rcp_f32_e32 v21, v19
	s_nop 0
	v_mul_f32_e32 v16, v16, v21
	v_lshlrev_b32_e32 v19, 16, v17
	v_mul_f32_e32 v20, 0xbfb8aa3b, v19
	v_exp_f32_e32 v20, v20
	v_and_b32_e32 v17, 0xffff0000, v17
	v_mul_f32_e32 v15, v15, v16
	v_cvt_pk_bf16_f32 v14, v14, v15
	v_add_f32_e32 v20, 1.0, v20
	v_rcp_f32_e32 v22, v20
	s_nop 0
	v_mul_f32_e32 v19, v19, v22
	v_mul_f32_e32 v20, 0xbfb8aa3b, v17
	v_exp_f32_e32 v20, v20
	v_mul_f32_e32 v12, v12, v19
	v_add_f32_e32 v20, 1.0, v20
	v_rcp_f32_e32 v22, v20
	s_nop 0
	v_mul_f32_e32 v17, v17, v22
	v_mul_f32_e32 v13, v13, v17
	v_cvt_pk_bf16_f32 v15, v12, v13
	global_load_dwordx2 v[12:13], v[4:5], off offset:192
	s_nop 0
	global_store_dwordx2 v[6:7], v[14:15], off offset:160
	s_waitcnt vmcnt(1)
	v_lshlrev_b32_e32 v14, 16, v12
	v_mul_f32_e32 v15, 0xbfb8aa3b, v14
	v_exp_f32_e32 v15, v15
	v_and_b32_e32 v12, 0xffff0000, v12
	v_add_f32_e32 v15, 1.0, v15
	v_rcp_f32_e32 v17, v15
	s_nop 0
	v_mul_f32_e32 v14, v14, v17
	v_mul_f32_e32 v15, 0xbfb8aa3b, v12
	v_exp_f32_e32 v15, v15
	v_mul_f32_e32 v10, v10, v14
	v_add_f32_e32 v15, 1.0, v15
	v_rcp_f32_e32 v17, v15
	s_nop 0
	v_mul_f32_e32 v15, v12, v17
	v_lshlrev_b32_e32 v12, 16, v13
	v_mul_f32_e32 v16, 0xbfb8aa3b, v12
	v_exp_f32_e32 v16, v16
	v_mul_f32_e32 v11, v11, v15
	v_cvt_pk_bf16_f32 v10, v10, v11
	v_add_f32_e32 v16, 1.0, v16
	v_rcp_f32_e32 v18, v16
	s_nop 0
	v_mul_f32_e32 v16, v12, v18
	v_and_b32_e32 v12, 0xffff0000, v13
	v_mul_f32_e32 v13, 0xbfb8aa3b, v12
	v_exp_f32_e32 v13, v13
	v_mul_f32_e32 v8, v8, v16
	v_add_f32_e32 v13, 1.0, v13
	v_rcp_f32_e32 v18, v13
	s_nop 0
	v_mul_f32_e32 v12, v12, v18
	v_mul_f32_e32 v9, v9, v12
	v_cvt_pk_bf16_f32 v11, v8, v9
	global_load_dwordx2 v[4:5], v[4:5], off offset:224
	s_waitcnt vmcnt(0)
	v_lshlrev_b32_e32 v8, 16, v4
	v_mul_f32_e32 v9, 0xbfb8aa3b, v8
	v_exp_f32_e32 v9, v9
	global_store_dwordx2 v[6:7], v[10:11], off offset:192
	v_and_b32_e32 v4, 0xffff0000, v4
	v_add_f32_e32 v9, 1.0, v9
	v_rcp_f32_e32 v11, v9
	s_nop 0
	v_mul_f32_e32 v8, v8, v11
	v_mul_f32_e32 v9, 0xbfb8aa3b, v4
	v_exp_f32_e32 v9, v9
	v_mul_f32_e32 v2, v2, v8
	v_add_f32_e32 v9, 1.0, v9
	v_rcp_f32_e32 v11, v9
	s_nop 0
	v_mul_f32_e32 v4, v4, v11
	v_lshlrev_b32_e32 v9, 16, v5
	v_mul_f32_e32 v10, 0xbfb8aa3b, v9
	v_exp_f32_e32 v10, v10
	v_and_b32_e32 v5, 0xffff0000, v5
	v_mul_f32_e32 v3, v3, v4
	v_cvt_pk_bf16_f32 v2, v2, v3
	v_add_f32_e32 v10, 1.0, v10
	v_rcp_f32_e32 v12, v10
	s_nop 0
	v_mul_f32_e32 v9, v9, v12
	v_mul_f32_e32 v10, 0xbfb8aa3b, v5
	v_exp_f32_e32 v10, v10
	v_mul_f32_e32 v0, v0, v9
	v_add_f32_e32 v10, 1.0, v10
	v_rcp_f32_e32 v12, v10
	s_nop 0
	v_mul_f32_e32 v5, v5, v12
	v_mul_f32_e32 v1, v1, v5
	v_cvt_pk_bf16_f32 v3, v0, v1
	global_store_dwordx2 v[6:7], v[2:3], off offset:224
	s_barrier
	s_cbranch_scc0 .LBB0_418

; __device__ __forceinline__ void xcd_barrier(const XcdBarrier& b) {
;     asm volatile("s_waitcnt vmcnt(0)" ::: "memory");
;     __syncthreads();
;     if (threadIdx.x == 0) {
;         unsigned* bar = b.bar;
;         __builtin_amdgcn_s_waitcnt(0);
;         unsigned nloc = b.st[0], nx = b.st[1];
;         if (nloc == 0u) { xcd_barrier_complete(bar, b.x, nloc, nx); b.st[0] = nloc; b.st[1] = nx; }
; __global__ void __launch_bounds__(NTHREADS, 2) fwd_kernel(Params KP) {
;     ...
;         if (ph + 1 < KP.ph_hi) { if (ph == KP.ph_lo) { asm volatile("s_waitcnt vmcnt(0)" ::: "memory"); __syncthreads(); cg::this_grid().sync(); __builtin_amdgcn_fence(__ATOMIC_ACQUIRE, "agent"); asm volatile("s_waitcnt vmcnt(0)" ::: "memory"); } else xcd_barrier(xbar); }
.LBB0_577:
	s_waitcnt vmcnt(0)
	s_barrier
	s_mov_b64 s[0:1], exec
	v_readlane_b32 s2, v252, 10
	v_readlane_b32 s3, v252, 11
	s_and_b64 s[2:3], s[0:1], s[2:3]
	s_mov_b64 exec, s[2:3]
	s_cbranch_execz .LBB0_661
	v_readlane_b32 s2, v252, 8
	s_waitcnt vmcnt(0) expcnt(0) lgkmcnt(0)
	s_nop 0
	v_mov_b32_e32 v0, s2
	ds_read_b32 v2, v0
	v_readlane_b32 s2, v252, 9
	s_waitcnt lgkmcnt(0)
	v_cmp_ne_u32_e32 vcc, 0, v2
	v_mov_b32_e32 v0, s2
	ds_read_b32 v0, v0
	s_cbranch_vccnz .LBB0_618
	v_readlane_b32 s4, v253, 9
	v_readlane_b32 s5, v253, 10
	s_load_dwordx2 s[2:3], s[4:5], 0x4
	v_readlane_b32 s4, v252, 38
	s_mov_b32 s9, 1
	s_waitcnt lgkmcnt(0)
	s_mul_i32 s8, s2, s4
	s_mul_i32 s8, s8, s3
	s_branch .LBB0_582
